# v086 + P7/last-phase epilogue stores also lane-transposed (data+address via ds_bpermute) so 4 adjacent lanes write 64 contiguous bytes
# baseline (speedup 1.0000x reference)
; #define G_STAGE(bufoff, gbase, voff) do { _Pragma("unroll") for (int _i = 0; _i < 2; ++_i) \
;         __builtin_amdgcn_global_load_lds((const unsigned*)((const char*)(gbase) + (voff)[_i]), (LAS unsigned*)(lds + (bufoff) + ldsw + _i * 8192), 16, 0, 0); } while (0)
; #define G_LDA(dst, b, h) do { _Pragma("unroll") for (int m = 0; m < 4; ++m) _Pragma("unroll") for (int k = 0; k < 2; ++k) dst[m][k] = *(const LAS bf16x8*)(lds + G_SA(b, h) + aoff + m * 2048 + k * 1024); } while (0)
; #define G_WAIT_V(n) asm volatile("s_waitcnt vmcnt(" #n ")" ::: "memory")
; #define G_WAIT_L(n) asm volatile("s_waitcnt lgkmcnt(" #n ")" ::: "memory")
; #define G_BAR __builtin_amdgcn_s_barrier()
; template <bool PERM, class Dec, class Epi>
; DI void gemm_phase(LAS unsigned char* lds, const int nM, const int nN, const int K, const int lda, const int ldb, const Dec& dec, const Epi& epi, const int vb, const int panel = -1) {
;     ...
;         for (int t = 0; t < nt; t += 2) {
;             const bool last = (t == nt - 2);
;             const char* a1 = cA + (size_t)(t + 1) * kstep;
;             const char* a2 = last ? nA : cA + (size_t)(t + 2) * kstep; const char* b2 = last ? nB : cB + (size_t)(t + 2) * kstep;
;             const char* a3 = a2 + kstep; const char* b3 = b2 + kstep;
;             G_LDB(B0, 0, 0); G_SCHED; G_LDA(At, 0, 0); G_STAGE(G_SA(1, 1), a1 + hstepA, voffA);
;             G_WAIT_L(8); G_BAR; G_WAIT_L(0); G_MMA(0, 0, At, B0); G_BAR; G_SCHED;
;             G_LDB(B1, 0, 1); G_STAGE(G_SB(0, 0), b2, voffB);
;             G_BAR; G_WAIT_L(0); G_MMA(0, 1, At, B1); G_BAR;
;             G_LDA(At, 0, 1); G_STAGE(G_SA(0, 0), a2, voffA);
;             G_BAR; G_WAIT_L(0); G_MMA(1, 0, At, B0); G_BAR; G_SCHED;
;             G_STAGE(G_SB(0, 1), b2 + hstepB, voffB);
;             G_WAIT_V(6); G_BAR; G_MMA(1, 1, At, B1); G_BAR;
;             G_LDB(B0, 1, 0); G_SCHED; G_LDA(At, 1, 0); G_STAGE(G_SA(0, 1), a2 + hstepA, voffA);
;             G_WAIT_L(8); G_BAR; G_WAIT_L(0); G_MMA(0, 0, At, B0); G_BAR; G_SCHED;
;             G_LDB(B1, 1, 1); G_STAGE(G_SB(1, 0), b3, voffB);
;             G_BAR; G_WAIT_L(0); G_MMA(0, 1, At, B1); G_BAR;
;             G_LDA(At, 1, 1); G_STAGE(G_SA(1, 0), a3, voffA);
;             G_BAR; G_WAIT_L(0); G_MMA(1, 0, At, B0); G_BAR; G_SCHED;
;             G_STAGE(G_SB(1, 1), b3 + hstepB, voffB);
;             G_WAIT_V(6); G_BAR; G_MMA(1, 1, At, B1); G_BAR;
;         }
.LBB0_670:
	s_add_u32 s50, s2, 0xfff80080
	s_addc_u32 s51, s3, -1
	s_add_i32 s64, 0, 0x10000
	v_add_u32_e32 v149, s64, v147
	ds_read_b128 v[142:145], v149
	ds_read_b128 v[150:153], v149 offset:1024
	ds_read_b128 v[154:157], v149 offset:2048
	ds_read_b128 v[158:161], v149 offset:3072
	s_cmp_eq_u32 s75, 28
	s_cselect_b32 s53, s35, s51
	s_cselect_b32 s52, s37, s50
	s_cselect_b32 s51, s71, s74
	s_cselect_b32 s50, s72, s73
	v_lshl_add_u64 v[198:199], s[2:3], 0, v[138:139]
	s_add_i32 m0, s54, 0xc000
	ds_read_b128 v[162:165], v148
	ds_read_b128 v[166:169], v148 offset:1024
	ds_read_b128 v[170:173], v148 offset:2048
	ds_read_b128 v[176:179], v148 offset:3072
	ds_read_b128 v[180:183], v148 offset:4096
	ds_read_b128 v[184:187], v148 offset:5120
	ds_read_b128 v[188:191], v148 offset:6144
	ds_read_b128 v[194:197], v148 offset:7168
	global_load_lds_dwordx4 v[198:199], off
	v_lshl_add_u64 v[198:199], s[2:3], 0, v[140:141]
	s_add_i32 m0, s54, 0xe000
	s_nop 0
	global_load_lds_dwordx4 v[198:199], off
	s_waitcnt lgkmcnt(8)
	s_barrier
	s_waitcnt lgkmcnt(0)
	s_setprio 1
	s_waitcnt lgkmcnt(0)
	v_mfma_f32_16x16x32_bf16 v[124:127], v[142:145], v[162:165], v[124:127]
	v_mfma_f32_16x16x32_bf16 v[120:123], v[154:157], v[162:165], v[120:123]
	v_mfma_f32_16x16x32_bf16 v[108:111], v[142:145], v[170:173], v[108:111]
	v_mfma_f32_16x16x32_bf16 v[104:107], v[154:157], v[170:173], v[104:107]
	v_mfma_f32_16x16x32_bf16 v[92:95], v[142:145], v[180:183], v[92:95]
	v_mfma_f32_16x16x32_bf16 v[88:91], v[154:157], v[180:183], v[88:91]
	v_mfma_f32_16x16x32_bf16 v[76:79], v[142:145], v[188:191], v[76:79]
	v_mfma_f32_16x16x32_bf16 v[72:75], v[154:157], v[188:191], v[72:75]
	v_mfma_f32_16x16x32_bf16 v[124:127], v[150:153], v[166:169], v[124:127]
	v_mfma_f32_16x16x32_bf16 v[120:123], v[158:161], v[166:169], v[120:123]
	v_mfma_f32_16x16x32_bf16 v[108:111], v[150:153], v[176:179], v[108:111]
	v_mfma_f32_16x16x32_bf16 v[104:107], v[158:161], v[176:179], v[104:107]
	v_mfma_f32_16x16x32_bf16 v[92:95], v[150:153], v[184:187], v[92:95]
	v_mfma_f32_16x16x32_bf16 v[88:91], v[158:161], v[184:187], v[88:91]
	v_mfma_f32_16x16x32_bf16 v[76:79], v[150:153], v[194:197], v[76:79]
	v_mfma_f32_16x16x32_bf16 v[72:75], v[158:161], v[194:197], v[72:75]
	s_setprio 0
	s_barrier
	s_add_i32 s68, 0, 0x14000
	s_add_i32 s64, s64, s39
	v_add_u32_e32 v149, s68, v147
	v_lshl_add_u64 v[214:215], s[50:51], 0, v[128:129]
	s_mov_b32 m0, s64
	ds_read_b128 v[198:201], v149
	ds_read_b128 v[202:205], v149 offset:1024
	ds_read_b128 v[206:209], v149 offset:2048
	ds_read_b128 v[210:213], v149 offset:3072
	global_load_lds_dwordx4 v[214:215], off
	v_lshl_add_u64 v[216:217], s[50:51], 0, v[134:135]
	s_add_i32 m0, s64, 0x2000
	s_nop 0
	global_load_lds_dwordx4 v[216:217], off
	s_barrier
	s_waitcnt lgkmcnt(0)
	s_setprio 1
	s_waitcnt lgkmcnt(0)
	v_mfma_f32_16x16x32_bf16 v[116:119], v[198:201], v[162:165], v[116:119]
	v_mfma_f32_16x16x32_bf16 v[112:115], v[206:209], v[162:165], v[112:115]
	v_mfma_f32_16x16x32_bf16 v[100:103], v[198:201], v[170:173], v[100:103]
	v_mfma_f32_16x16x32_bf16 v[96:99], v[206:209], v[170:173], v[96:99]
	v_mfma_f32_16x16x32_bf16 v[84:87], v[198:201], v[180:183], v[84:87]
	v_mfma_f32_16x16x32_bf16 v[80:83], v[206:209], v[180:183], v[80:83]
	v_mfma_f32_16x16x32_bf16 v[68:71], v[198:201], v[188:191], v[68:71]
	v_mfma_f32_16x16x32_bf16 v[64:67], v[206:209], v[188:191], v[64:67]
	v_mfma_f32_16x16x32_bf16 v[116:119], v[202:205], v[166:169], v[116:119]
	v_mfma_f32_16x16x32_bf16 v[112:115], v[210:213], v[166:169], v[112:115]
	v_mfma_f32_16x16x32_bf16 v[100:103], v[202:205], v[176:179], v[100:103]
	v_mfma_f32_16x16x32_bf16 v[96:99], v[210:213], v[176:179], v[96:99]
	v_mfma_f32_16x16x32_bf16 v[84:87], v[202:205], v[184:187], v[84:87]
	v_mfma_f32_16x16x32_bf16 v[80:83], v[210:213], v[184:187], v[80:83]
	v_mfma_f32_16x16x32_bf16 v[68:71], v[202:205], v[194:197], v[68:71]
	v_mfma_f32_16x16x32_bf16 v[64:67], v[210:213], v[194:197], v[64:67]
	s_setprio 0
	s_mov_b32 m0, s54
	v_lshl_add_u64 v[218:219], s[52:53], 0, v[128:129]
	s_barrier
	ds_read_b128 v[162:165], v148 offset:16384
	ds_read_b128 v[166:169], v148 offset:17408
	ds_read_b128 v[170:173], v148 offset:18432
	ds_read_b128 v[176:179], v148 offset:19456
	ds_read_b128 v[180:183], v148 offset:20480
	ds_read_b128 v[184:187], v148 offset:21504
	ds_read_b128 v[188:191], v148 offset:22528
	ds_read_b128 v[194:197], v148 offset:23552
	global_load_lds_dwordx4 v[218:219], off
	v_lshl_add_u64 v[220:221], s[52:53], 0, v[134:135]
	s_mov_b32 m0, s55
	s_nop 0
	global_load_lds_dwordx4 v[220:221], off
	s_barrier
	s_waitcnt lgkmcnt(0)
	s_setprio 1
	s_waitcnt lgkmcnt(0)
	v_mfma_f32_16x16x32_bf16 v[60:63], v[142:145], v[162:165], v[60:63]
	v_mfma_f32_16x16x32_bf16 v[56:59], v[154:157], v[162:165], v[56:59]
	v_mfma_f32_16x16x32_bf16 v[44:47], v[142:145], v[170:173], v[44:47]
	v_mfma_f32_16x16x32_bf16 v[40:43], v[154:157], v[170:173], v[40:43]
	v_mfma_f32_16x16x32_bf16 v[28:31], v[142:145], v[180:183], v[28:31]
	v_mfma_f32_16x16x32_bf16 v[24:27], v[154:157], v[180:183], v[24:27]
	v_mfma_f32_16x16x32_bf16 v[12:15], v[142:145], v[188:191], v[12:15]
	v_mfma_f32_16x16x32_bf16 v[8:11], v[154:157], v[188:191], v[8:11]
	v_mfma_f32_16x16x32_bf16 v[60:63], v[150:153], v[166:169], v[60:63]
	v_mfma_f32_16x16x32_bf16 v[56:59], v[158:161], v[166:169], v[56:59]
	v_mfma_f32_16x16x32_bf16 v[44:47], v[150:153], v[176:179], v[44:47]
	v_mfma_f32_16x16x32_bf16 v[40:43], v[158:161], v[176:179], v[40:43]
	v_mfma_f32_16x16x32_bf16 v[28:31], v[150:153], v[184:187], v[28:31]
	v_mfma_f32_16x16x32_bf16 v[24:27], v[158:161], v[184:187], v[24:27]
	v_mfma_f32_16x16x32_bf16 v[12:15], v[150:153], v[194:197], v[12:15]
	v_mfma_f32_16x16x32_bf16 v[8:11], v[158:161], v[194:197], v[8:11]
	s_setprio 0
	s_barrier
; #define G_STAGE(bufoff, gbase, voff) do { _Pragma("unroll") for (int _i = 0; _i < 2; ++_i) \
;         __builtin_amdgcn_global_load_lds((const unsigned*)((const char*)(gbase) + (voff)[_i]), (LAS unsigned*)(lds + (bufoff) + ldsw + _i * 8192), 16, 0, 0); } while (0)
; #define G_LDA(dst, b, h) do { _Pragma("unroll") for (int m = 0; m < 4; ++m) _Pragma("unroll") for (int k = 0; k < 2; ++k) dst[m][k] = *(const LAS bf16x8*)(lds + G_SA(b, h) + aoff + m * 2048 + k * 1024); } while (0)
; #define G_LDB(dst, b, h) do { _Pragma("unroll") for (int n = 0; n < 2; ++n) _Pragma("unroll") for (int k = 0; k < 2; ++k) dst[n][k] = *(const LAS bf16x8*)(lds + G_SB(b, h) + boff + n * 2048 + k * 1024); } while (0)
; #define G_WAIT_V(n) asm volatile("s_waitcnt vmcnt(" #n ")" ::: "memory")
; #define G_WAIT_L(n) asm volatile("s_waitcnt lgkmcnt(" #n ")" ::: "memory")
; #define G_BAR __builtin_amdgcn_s_barrier()
; #define G_SCHED __builtin_amdgcn_sched_barrier(0)
; template <bool PERM, class Dec, class Epi>
; DI void gemm_phase(LAS unsigned char* lds, const int nM, const int nN, const int K, const int lda, const int ldb, const Dec& dec, const Epi& epi, const int vb, const int panel = -1) {
;     ...
;             G_LDB(B0, 0, 0); G_SCHED; G_LDA(At, 0, 0); G_STAGE(G_SA(1, 1), a1 + hstepA, voffA);
;             G_WAIT_L(8); G_BAR; G_WAIT_L(0); G_MMA(0, 0, At, B0); G_BAR; G_SCHED;
;             G_LDB(B1, 0, 1); G_STAGE(G_SB(0, 0), b2, voffB);
;             G_BAR; G_WAIT_L(0); G_MMA(0, 1, At, B1); G_BAR;
;             G_LDA(At, 0, 1); G_STAGE(G_SA(0, 0), a2, voffA);
;             G_BAR; G_WAIT_L(0); G_MMA(1, 0, At, B0); G_BAR; G_SCHED;
;             G_STAGE(G_SB(0, 1), b2 + hstepB, voffB);
;             G_WAIT_V(6); G_BAR; G_MMA(1, 1, At, B1); G_BAR;
;             G_LDB(B0, 1, 0); G_SCHED; G_LDA(At, 1, 0); G_STAGE(G_SA(0, 1), a2 + hstepA, voffA);
;             G_WAIT_L(8); G_BAR; G_WAIT_L(0); G_MMA(0, 0, At, B0); G_BAR; G_SCHED;
;             G_LDB(B1, 1, 1); G_STAGE(G_SB(1, 0), b3, voffB);
;             G_BAR; G_WAIT_L(0); G_MMA(0, 1, At, B1); G_BAR;
;             G_LDA(At, 1, 1); G_STAGE(G_SA(1, 0), a3, voffA);
;             G_BAR; G_WAIT_L(0); G_MMA(1, 0, At, B0); G_BAR; G_SCHED;
;             G_STAGE(G_SB(1, 1), b3 + hstepB, voffB);
;             G_WAIT_V(6); G_BAR; G_MMA(1, 1, At, B1); G_BAR;
	s_add_u32 s64, s50, 0x80000
	s_addc_u32 s65, s51, 0
	s_add_i32 s68, s68, s39
	v_lshl_add_u64 v[142:143], s[64:65], 0, v[128:129]
	s_mov_b32 m0, s68
	s_nop 0
	global_load_lds_dwordx4 v[142:143], off
	v_lshl_add_u64 v[142:143], s[64:65], 0, v[134:135]
	s_add_i32 m0, s68, 0x2000
	s_nop 0
	global_load_lds_dwordx4 v[142:143], off
	s_waitcnt vmcnt(6)
	s_barrier
	s_setprio 1
	v_mfma_f32_16x16x32_bf16 v[52:55], v[198:201], v[162:165], v[52:55]
	v_mfma_f32_16x16x32_bf16 v[48:51], v[206:209], v[162:165], v[48:51]
	v_mfma_f32_16x16x32_bf16 v[36:39], v[198:201], v[170:173], v[36:39]
	v_mfma_f32_16x16x32_bf16 v[32:35], v[206:209], v[170:173], v[32:35]
	v_mfma_f32_16x16x32_bf16 v[20:23], v[198:201], v[180:183], v[20:23]
	v_mfma_f32_16x16x32_bf16 v[16:19], v[206:209], v[180:183], v[16:19]
	v_mfma_f32_16x16x32_bf16 v[4:7], v[198:201], v[188:191], v[4:7]
	v_mfma_f32_16x16x32_bf16 v[0:3], v[206:209], v[188:191], v[0:3]
	v_mfma_f32_16x16x32_bf16 v[52:55], v[202:205], v[166:169], v[52:55]
	v_mfma_f32_16x16x32_bf16 v[48:51], v[210:213], v[166:169], v[48:51]
	v_mfma_f32_16x16x32_bf16 v[36:39], v[202:205], v[176:179], v[36:39]
	v_mfma_f32_16x16x32_bf16 v[32:35], v[210:213], v[176:179], v[32:35]
	v_mfma_f32_16x16x32_bf16 v[20:23], v[202:205], v[184:187], v[20:23]
	v_mfma_f32_16x16x32_bf16 v[16:19], v[210:213], v[184:187], v[16:19]
	v_mfma_f32_16x16x32_bf16 v[4:7], v[202:205], v[194:197], v[4:7]
	v_mfma_f32_16x16x32_bf16 v[0:3], v[210:213], v[194:197], v[0:3]
	s_setprio 0
	s_add_i32 s64, 0, 0x18000
	v_add_u32_e32 v149, s64, v147
	s_barrier
	ds_read_b128 v[142:145], v149
	ds_read_b128 v[150:153], v149 offset:1024
	ds_read_b128 v[154:157], v149 offset:2048
	ds_read_b128 v[158:161], v149 offset:3072
	s_add_u32 s52, s52, 0x80000
	s_addc_u32 s53, s53, 0
	s_mov_b32 m0, s58
	v_lshl_add_u64 v[198:199], s[52:53], 0, v[128:129]
	ds_read_b128 v[162:165], v148 offset:32768
	ds_read_b128 v[166:169], v148 offset:33792
	ds_read_b128 v[170:173], v148 offset:34816
	ds_read_b128 v[176:179], v148 offset:35840
	ds_read_b128 v[180:183], v148 offset:36864
	ds_read_b128 v[184:187], v148 offset:37888
	ds_read_b128 v[188:191], v148 offset:38912
	ds_read_b128 v[194:197], v148 offset:39936
	global_load_lds_dwordx4 v[198:199], off
	v_lshl_add_u64 v[198:199], s[52:53], 0, v[134:135]
	s_mov_b32 m0, s59
	s_nop 0
	global_load_lds_dwordx4 v[198:199], off
	s_waitcnt lgkmcnt(8)
	s_barrier
	s_waitcnt lgkmcnt(0)
	s_setprio 1
	s_waitcnt lgkmcnt(0)
	v_mfma_f32_16x16x32_bf16 v[124:127], v[142:145], v[162:165], v[124:127]
	v_mfma_f32_16x16x32_bf16 v[120:123], v[154:157], v[162:165], v[120:123]
	v_mfma_f32_16x16x32_bf16 v[108:111], v[142:145], v[170:173], v[108:111]
	v_mfma_f32_16x16x32_bf16 v[104:107], v[154:157], v[170:173], v[104:107]
	v_mfma_f32_16x16x32_bf16 v[92:95], v[142:145], v[180:183], v[92:95]
	v_mfma_f32_16x16x32_bf16 v[88:91], v[154:157], v[180:183], v[88:91]
	v_mfma_f32_16x16x32_bf16 v[76:79], v[142:145], v[188:191], v[76:79]
	v_mfma_f32_16x16x32_bf16 v[72:75], v[154:157], v[188:191], v[72:75]
	v_mfma_f32_16x16x32_bf16 v[124:127], v[150:153], v[166:169], v[124:127]
	v_mfma_f32_16x16x32_bf16 v[120:123], v[158:161], v[166:169], v[120:123]
	v_mfma_f32_16x16x32_bf16 v[108:111], v[150:153], v[176:179], v[108:111]
	v_mfma_f32_16x16x32_bf16 v[104:107], v[158:161], v[176:179], v[104:107]
	v_mfma_f32_16x16x32_bf16 v[92:95], v[150:153], v[184:187], v[92:95]
	v_mfma_f32_16x16x32_bf16 v[88:91], v[158:161], v[184:187], v[88:91]
	v_mfma_f32_16x16x32_bf16 v[76:79], v[150:153], v[194:197], v[76:79]
	v_mfma_f32_16x16x32_bf16 v[72:75], v[158:161], v[194:197], v[72:75]
	s_setprio 0
	s_barrier
	s_add_i32 s52, 0, 0x1c000
	s_add_i32 s53, s64, s39
	v_add_u32_e32 v149, s52, v147
	v_lshl_add_u64 v[214:215], v[214:215], 0, s[30:31]
	s_mov_b32 m0, s53
	ds_read_b128 v[198:201], v149
	ds_read_b128 v[202:205], v149 offset:1024
	ds_read_b128 v[206:209], v149 offset:2048
	ds_read_b128 v[210:213], v149 offset:3072
	global_load_lds_dwordx4 v[214:215], off
	v_lshl_add_u64 v[214:215], v[216:217], 0, s[30:31]
	s_add_i32 m0, s53, 0x2000
	s_nop 0
	global_load_lds_dwordx4 v[214:215], off
	s_barrier
	s_waitcnt lgkmcnt(0)
	s_setprio 1
	s_waitcnt lgkmcnt(0)
	v_mfma_f32_16x16x32_bf16 v[116:119], v[198:201], v[162:165], v[116:119]
	v_mfma_f32_16x16x32_bf16 v[112:115], v[206:209], v[162:165], v[112:115]
	v_mfma_f32_16x16x32_bf16 v[100:103], v[198:201], v[170:173], v[100:103]
	v_mfma_f32_16x16x32_bf16 v[96:99], v[206:209], v[170:173], v[96:99]
	v_mfma_f32_16x16x32_bf16 v[84:87], v[198:201], v[180:183], v[84:87]
	v_mfma_f32_16x16x32_bf16 v[80:83], v[206:209], v[180:183], v[80:83]
	v_mfma_f32_16x16x32_bf16 v[68:71], v[198:201], v[188:191], v[68:71]
	v_mfma_f32_16x16x32_bf16 v[64:67], v[206:209], v[188:191], v[64:67]
	v_mfma_f32_16x16x32_bf16 v[116:119], v[202:205], v[166:169], v[116:119]
	v_mfma_f32_16x16x32_bf16 v[112:115], v[210:213], v[166:169], v[112:115]
	v_mfma_f32_16x16x32_bf16 v[100:103], v[202:205], v[176:179], v[100:103]
	v_mfma_f32_16x16x32_bf16 v[96:99], v[210:213], v[176:179], v[96:99]
	v_mfma_f32_16x16x32_bf16 v[84:87], v[202:205], v[184:187], v[84:87]
	v_mfma_f32_16x16x32_bf16 v[80:83], v[210:213], v[184:187], v[80:83]
	v_mfma_f32_16x16x32_bf16 v[68:71], v[202:205], v[194:197], v[68:71]
	v_mfma_f32_16x16x32_bf16 v[64:67], v[210:213], v[194:197], v[64:67]
	s_setprio 0
	s_mov_b32 m0, s62
	v_lshl_add_u64 v[214:215], v[218:219], 0, s[30:31]
	s_barrier
	ds_read_b128 v[162:165], v148 offset:49152
	ds_read_b128 v[166:169], v148 offset:50176
	ds_read_b128 v[170:173], v148 offset:51200
	ds_read_b128 v[176:179], v148 offset:52224
	ds_read_b128 v[180:183], v148 offset:53248
	ds_read_b128 v[184:187], v148 offset:54272
	ds_read_b128 v[188:191], v148 offset:55296
	ds_read_b128 v[194:197], v148 offset:56320
	global_load_lds_dwordx4 v[214:215], off
	v_lshl_add_u64 v[214:215], v[220:221], 0, s[30:31]
	s_mov_b32 m0, s63
	s_nop 0
	global_load_lds_dwordx4 v[214:215], off
	s_barrier
; #define G_STAGE(bufoff, gbase, voff) do { _Pragma("unroll") for (int _i = 0; _i < 2; ++_i) \
;         __builtin_amdgcn_global_load_lds((const unsigned*)((const char*)(gbase) + (voff)[_i]), (LAS unsigned*)(lds + (bufoff) + ldsw + _i * 8192), 16, 0, 0); } while (0)
; #define G_LDA(dst, b, h) do { _Pragma("unroll") for (int m = 0; m < 4; ++m) _Pragma("unroll") for (int k = 0; k < 2; ++k) dst[m][k] = *(const LAS bf16x8*)(lds + G_SA(b, h) + aoff + m * 2048 + k * 1024); } while (0)
; #define G_MMA(ai, bj, At, Bt) do { __builtin_amdgcn_s_setprio(1); _Pragma("unroll") for (int m = 0; m < 4; ++m) _Pragma("unroll") for (int n = 0; n < 2; ++n) _Pragma("unroll") for (int k = 0; k < 2; ++k) \
;         acc[ai][bj][m][n] = __builtin_amdgcn_mfma_f32_16x16x32_bf16(Bt[n][k], At[m][k], acc[ai][bj][m][n], 0, 0, 0); __builtin_amdgcn_s_setprio(0); } while (0)
; #define G_WAIT_V(n) asm volatile("s_waitcnt vmcnt(" #n ")" ::: "memory")
; #define G_WAIT_L(n) asm volatile("s_waitcnt lgkmcnt(" #n ")" ::: "memory")
; #define G_BAR __builtin_amdgcn_s_barrier()
; #define G_SCHED __builtin_amdgcn_sched_barrier(0)
; template <bool PERM, class Dec, class Epi>
; DI void gemm_phase(LAS unsigned char* lds, const int nM, const int nN, const int K, const int lda, const int ldb, const Dec& dec, const Epi& epi, const int vb, const int panel = -1) {
;     ...
;             G_BAR; G_WAIT_L(0); G_MMA(0, 1, At, B1); G_BAR;
;             G_LDA(At, 1, 1); G_STAGE(G_SA(1, 0), a3, voffA);
;             G_BAR; G_WAIT_L(0); G_MMA(1, 0, At, B0); G_BAR; G_SCHED;
;             G_STAGE(G_SB(1, 1), b3 + hstepB, voffB);
;             G_WAIT_V(6); G_BAR; G_MMA(1, 1, At, B1); G_BAR;
;         }
; __global__ void __launch_bounds__(512) hybrid_fwd(Params p) {
;     ...
;                   for (int m = 0; m < 4; ++m) { const int row = pm * 256 + ai * 128 + wr * 64 + m * 16 + fr; const size_t ro = (size_t)row * 1024 + pn * 256 + wc * 32 + 4 * fq;
;                       float ssq = 0.f;
; #pragma unroll
;                       for (int bj = 0; bj < 2; ++bj)
; #pragma unroll
;                           for (int n = 0; n < 2; ++n) { const size_t o = ro + bj * 128 + n * 16; const f32x4 v = *(const f32x4*)(X + o) + acc[ai][bj][m][n];
	s_waitcnt lgkmcnt(0)
	s_setprio 1
	s_waitcnt lgkmcnt(0)
	v_mfma_f32_16x16x32_bf16 v[60:63], v[142:145], v[162:165], v[60:63]
	v_mfma_f32_16x16x32_bf16 v[56:59], v[154:157], v[162:165], v[56:59]
	v_mfma_f32_16x16x32_bf16 v[44:47], v[142:145], v[170:173], v[44:47]
	v_mfma_f32_16x16x32_bf16 v[40:43], v[154:157], v[170:173], v[40:43]
	v_mfma_f32_16x16x32_bf16 v[28:31], v[142:145], v[180:183], v[28:31]
	v_mfma_f32_16x16x32_bf16 v[24:27], v[154:157], v[180:183], v[24:27]
	v_mfma_f32_16x16x32_bf16 v[12:15], v[142:145], v[188:191], v[12:15]
	v_mfma_f32_16x16x32_bf16 v[8:11], v[154:157], v[188:191], v[8:11]
	v_mfma_f32_16x16x32_bf16 v[60:63], v[150:153], v[166:169], v[60:63]
	v_mfma_f32_16x16x32_bf16 v[56:59], v[158:161], v[166:169], v[56:59]
	v_mfma_f32_16x16x32_bf16 v[44:47], v[150:153], v[176:179], v[44:47]
	v_mfma_f32_16x16x32_bf16 v[40:43], v[158:161], v[176:179], v[40:43]
	v_mfma_f32_16x16x32_bf16 v[28:31], v[150:153], v[184:187], v[28:31]
	v_mfma_f32_16x16x32_bf16 v[24:27], v[158:161], v[184:187], v[24:27]
	v_mfma_f32_16x16x32_bf16 v[12:15], v[150:153], v[194:197], v[12:15]
	v_mfma_f32_16x16x32_bf16 v[8:11], v[158:161], v[194:197], v[8:11]
	s_setprio 0
	s_barrier
	s_add_u32 s50, s50, 0x80080
	s_addc_u32 s51, s51, 0
	s_add_i32 s52, s52, s39
	v_lshl_add_u64 v[142:143], s[50:51], 0, v[128:129]
	s_mov_b32 m0, s52
	s_nop 0
	global_load_lds_dwordx4 v[142:143], off
	v_lshl_add_u64 v[142:143], s[50:51], 0, v[134:135]
	s_add_i32 m0, s52, 0x2000
	s_nop 0
	global_load_lds_dwordx4 v[142:143], off
	s_waitcnt vmcnt(6)
	s_barrier
	s_setprio 1
	v_mfma_f32_16x16x32_bf16 v[52:55], v[198:201], v[162:165], v[52:55]
	v_mfma_f32_16x16x32_bf16 v[48:51], v[206:209], v[162:165], v[48:51]
	v_mfma_f32_16x16x32_bf16 v[36:39], v[198:201], v[170:173], v[36:39]
	v_mfma_f32_16x16x32_bf16 v[32:35], v[206:209], v[170:173], v[32:35]
	v_mfma_f32_16x16x32_bf16 v[20:23], v[198:201], v[180:183], v[20:23]
	v_mfma_f32_16x16x32_bf16 v[16:19], v[206:209], v[180:183], v[16:19]
	v_mfma_f32_16x16x32_bf16 v[4:7], v[198:201], v[188:191], v[4:7]
	v_mfma_f32_16x16x32_bf16 v[0:3], v[206:209], v[188:191], v[0:3]
	v_mfma_f32_16x16x32_bf16 v[52:55], v[202:205], v[166:169], v[52:55]
	v_mfma_f32_16x16x32_bf16 v[48:51], v[210:213], v[166:169], v[48:51]
	v_mfma_f32_16x16x32_bf16 v[36:39], v[202:205], v[176:179], v[36:39]
	v_mfma_f32_16x16x32_bf16 v[32:35], v[210:213], v[176:179], v[32:35]
	v_mfma_f32_16x16x32_bf16 v[20:23], v[202:205], v[184:187], v[20:23]
	v_mfma_f32_16x16x32_bf16 v[16:19], v[210:213], v[184:187], v[16:19]
	v_mfma_f32_16x16x32_bf16 v[4:7], v[202:205], v[194:197], v[4:7]
	v_mfma_f32_16x16x32_bf16 v[0:3], v[210:213], v[194:197], v[0:3]
	s_setprio 0
	s_add_i32 s75, s75, 2
	s_add_u32 s2, s2, 0x100
	s_addc_u32 s3, s3, 0
	s_add_u32 s73, s73, 0x100
	s_addc_u32 s74, s74, 0
	s_cmp_gt_u32 s75, 29
	s_barrier
	s_cbranch_scc0 .LBB0_670
	v_and_b32_e32 v149, 64, v174
	v_xor_b32_e32 v145, 16, v174
	v_add_u32_e32 v149, 64, v149
	v_cmp_lt_i32_e32 vcc, v145, v149
	v_lshl_add_u32 v144, s67, 8, v146
	s_lshl_b32 s2, s70, 8
	v_cndmask_b32_e32 v145, v174, v145, vcc
	v_lshlrev_b32_e32 v150, 2, v145
	v_xor_b32_e32 v145, 32, v174
	v_cmp_lt_i32_e32 vcc, v145, v149
	s_ashr_i32 s3, s2, 31
	v_mov_b32_e32 v143, s3
	v_cndmask_b32_e32 v145, v174, v145, vcc
	v_lshlrev_b32_e32 v149, 2, v145
	v_ashrrev_i32_e32 v145, 31, v144
	v_or_b32_e32 v142, s2, v136
	v_lshlrev_b64 v[152:153], 10, v[144:145]
	v_readlane_b32 s0, v246, 53
	v_lshl_add_u64 v[156:157], v[152:153], 0, v[142:143]
	v_readlane_b32 s1, v246, 54
	v_readlane_b32 s2, v246, 55
	v_readlane_b32 s3, v246, 56
	v_lshl_add_u64 v[158:159], v[156:157], 2, s[0:1]
	global_load_dwordx4 v[160:163], v[158:159], off
	global_load_dwordx4 v[164:167], v[158:159], off offset:64
	global_load_dwordx4 v[168:171], v[158:159], off offset:512
	global_load_dwordx4 v[176:179], v[158:159], off offset:576
	v_add_co_u32_e32 v214, vcc, 0x10000, v158
	s_nop 1
	v_addc_co_u32_e32 v215, vcc, 0, v159, vcc
	global_load_dwordx4 v[180:183], v[214:215], off
	global_load_dwordx4 v[184:187], v[214:215], off offset:64
	global_load_dwordx4 v[188:191], v[214:215], off offset:512
	global_load_dwordx4 v[194:197], v[214:215], off offset:576
	v_add_co_u32_e32 v214, vcc, 0x20000, v158
	s_nop 1
	v_addc_co_u32_e32 v215, vcc, 0, v159, vcc
	global_load_dwordx4 v[198:201], v[214:215], off
	global_load_dwordx4 v[202:205], v[214:215], off offset:64
	global_load_dwordx4 v[206:209], v[214:215], off offset:512
	global_load_dwordx4 v[210:213], v[214:215], off offset:576
	s_waitcnt vmcnt(8)
	v_pk_add_f32 v[124:125], v[124:125], v[160:161]
	v_pk_add_f32 v[126:127], v[126:127], v[162:163]
	v_pk_add_f32 v[120:121], v[120:121], v[164:165]
	v_pk_add_f32 v[122:123], v[122:123], v[166:167]
	v_pk_add_f32 v[116:117], v[116:117], v[168:169]
	v_pk_add_f32 v[118:119], v[118:119], v[170:171]
	v_pk_add_f32 v[112:113], v[112:113], v[176:177]
	v_pk_add_f32 v[114:115], v[114:115], v[178:179]
	v_add_co_u32_e32 v214, vcc, 0x30000, v158
	s_nop 1
	v_addc_co_u32_e32 v215, vcc, 0, v159, vcc
	global_load_dwordx4 v[160:163], v[214:215], off
	global_load_dwordx4 v[164:167], v[214:215], off offset:64
	global_load_dwordx4 v[168:171], v[214:215], off offset:512
	global_load_dwordx4 v[176:179], v[214:215], off offset:576
	s_waitcnt vmcnt(8)
	v_pk_add_f32 v[108:109], v[108:109], v[180:181]
	v_pk_add_f32 v[110:111], v[110:111], v[182:183]
	v_pk_add_f32 v[104:105], v[104:105], v[184:185]
	v_pk_add_f32 v[106:107], v[106:107], v[186:187]
	v_pk_add_f32 v[100:101], v[100:101], v[188:189]
	v_pk_add_f32 v[102:103], v[102:103], v[190:191]
	v_pk_add_f32 v[96:97], v[96:97], v[194:195]
	v_pk_add_f32 v[98:99], v[98:99], v[196:197]
	v_add_co_u32_e32 v214, vcc, 0x80000, v158
	s_nop 1
	v_addc_co_u32_e32 v215, vcc, 0, v159, vcc
	global_load_dwordx4 v[180:183], v[214:215], off
	global_load_dwordx4 v[184:187], v[214:215], off offset:64
	global_load_dwordx4 v[188:191], v[214:215], off offset:512
	global_load_dwordx4 v[194:197], v[214:215], off offset:576
	s_waitcnt vmcnt(8)
; DI unsigned pk2(float a, float b) { f32x2 v = {a, b}; bf2_t r = __builtin_convertvector(v, bf2_t); return __builtin_bit_cast(unsigned, r); }
; __global__ void __launch_bounds__(512) hybrid_fwd(Params p) {
;     ...
;                   for (int m = 0; m < 4; ++m) { const int row = pm * 256 + ai * 128 + wr * 64 + m * 16 + fr; const size_t ro = (size_t)row * 1024 + pn * 256 + wc * 32 + 4 * fq;
;                       float ssq = 0.f;
; #pragma unroll
;                       for (int bj = 0; bj < 2; ++bj)
; #pragma unroll
;                           for (int n = 0; n < 2; ++n) { const size_t o = ro + bj * 128 + n * 16; const f32x4 v = *(const f32x4*)(X + o) + acc[ai][bj][m][n];
;                               u32x2 wv; wv[0] = pk2(v[0], v[1]); wv[1] = pk2(v[2], v[3]); *(u32x2*)(U + o) = wv;
;                               ssq += v[0] * v[0] + v[1] * v[1] + v[2] * v[2] + v[3] * v[3]; }
;                       ssq += __shfl_xor(ssq, 16); ssq += __shfl_xor(ssq, 32);
;                       if (fq == 0) unsafeAtomicAdd(SS1 + row, ssq); } }, vb); }
	v_pk_add_f32 v[92:93], v[92:93], v[198:199]
	v_pk_add_f32 v[94:95], v[94:95], v[200:201]
	v_pk_add_f32 v[88:89], v[88:89], v[202:203]
	v_pk_add_f32 v[90:91], v[90:91], v[204:205]
	v_pk_add_f32 v[84:85], v[84:85], v[206:207]
	v_pk_add_f32 v[86:87], v[86:87], v[208:209]
	v_pk_add_f32 v[80:81], v[80:81], v[210:211]
	v_pk_add_f32 v[82:83], v[82:83], v[212:213]
	v_add_co_u32_e32 v214, vcc, 0x90000, v158
	s_nop 1
	v_addc_co_u32_e32 v215, vcc, 0, v159, vcc
	global_load_dwordx4 v[198:201], v[214:215], off
	global_load_dwordx4 v[202:205], v[214:215], off offset:64
	global_load_dwordx4 v[206:209], v[214:215], off offset:512
	global_load_dwordx4 v[210:213], v[214:215], off offset:576
	s_waitcnt vmcnt(8)
	v_pk_add_f32 v[76:77], v[76:77], v[160:161]
	v_pk_add_f32 v[78:79], v[78:79], v[162:163]
	v_pk_add_f32 v[72:73], v[72:73], v[164:165]
	v_pk_add_f32 v[74:75], v[74:75], v[166:167]
	v_pk_add_f32 v[68:69], v[68:69], v[168:169]
	v_pk_add_f32 v[70:71], v[70:71], v[170:171]
	v_pk_add_f32 v[64:65], v[64:65], v[176:177]
	v_pk_add_f32 v[66:67], v[66:67], v[178:179]
	v_add_co_u32_e32 v214, vcc, 0xa0000, v158
	s_nop 1
	v_addc_co_u32_e32 v215, vcc, 0, v159, vcc
	global_load_dwordx4 v[160:163], v[214:215], off
	global_load_dwordx4 v[164:167], v[214:215], off offset:64
	global_load_dwordx4 v[168:171], v[214:215], off offset:512
	global_load_dwordx4 v[176:179], v[214:215], off offset:576
	s_waitcnt vmcnt(8)
	v_pk_add_f32 v[60:61], v[60:61], v[180:181]
	v_pk_add_f32 v[62:63], v[62:63], v[182:183]
	v_pk_add_f32 v[56:57], v[56:57], v[184:185]
	v_pk_add_f32 v[58:59], v[58:59], v[186:187]
	v_pk_add_f32 v[52:53], v[52:53], v[188:189]
	v_pk_add_f32 v[54:55], v[54:55], v[190:191]
	v_pk_add_f32 v[48:49], v[48:49], v[194:195]
	v_pk_add_f32 v[50:51], v[50:51], v[196:197]
	v_add_co_u32_e32 v214, vcc, 0xb0000, v158
	s_nop 1
	v_addc_co_u32_e32 v215, vcc, 0, v159, vcc
	global_load_dwordx4 v[180:183], v[214:215], off
	global_load_dwordx4 v[184:187], v[214:215], off offset:64
	global_load_dwordx4 v[188:191], v[214:215], off offset:512
	global_load_dwordx4 v[194:197], v[214:215], off offset:576
	s_waitcnt vmcnt(8)
	v_pk_add_f32 v[44:45], v[44:45], v[198:199]
	v_pk_add_f32 v[46:47], v[46:47], v[200:201]
	v_pk_add_f32 v[40:41], v[40:41], v[202:203]
	v_pk_add_f32 v[42:43], v[42:43], v[204:205]
	v_pk_add_f32 v[36:37], v[36:37], v[206:207]
	v_pk_add_f32 v[38:39], v[38:39], v[208:209]
	v_pk_add_f32 v[32:33], v[32:33], v[210:211]
	v_pk_add_f32 v[34:35], v[34:35], v[212:213]
	s_waitcnt vmcnt(4)
	v_pk_add_f32 v[28:29], v[28:29], v[160:161]
	v_pk_add_f32 v[30:31], v[30:31], v[162:163]
	v_pk_add_f32 v[24:25], v[24:25], v[164:165]
	v_pk_add_f32 v[26:27], v[26:27], v[166:167]
	v_pk_add_f32 v[20:21], v[20:21], v[168:169]
	v_pk_add_f32 v[22:23], v[22:23], v[170:171]
	v_pk_add_f32 v[16:17], v[16:17], v[176:177]
	v_pk_add_f32 v[18:19], v[18:19], v[178:179]
	s_waitcnt vmcnt(0)
	v_pk_add_f32 v[12:13], v[12:13], v[180:181]
	v_pk_add_f32 v[14:15], v[14:15], v[182:183]
	v_pk_add_f32 v[8:9], v[8:9], v[184:185]
	v_pk_add_f32 v[10:11], v[10:11], v[186:187]
	v_pk_add_f32 v[4:5], v[4:5], v[188:189]
	v_pk_add_f32 v[6:7], v[6:7], v[190:191]
	v_pk_add_f32 v[0:1], v[0:1], v[194:195]
	v_pk_add_f32 v[2:3], v[2:3], v[196:197]
	v_mbcnt_lo_u32_b32 v210, -1, 0
	v_mbcnt_hi_u32_b32 v210, -1, v210
	v_and_b32_e32 v212, 1, v210
	v_lshlrev_b32_e32 v212, 5, v212
	v_bfe_u32 v213, v210, 1, 1
	v_lshl_or_b32 v212, v213, 4, v212
	v_lshrrev_b32_e32 v210, 2, v210
	v_add_lshl_u32 v210, v210, v212, 2
	v_mbcnt_lo_u32_b32 v212, -1, 0
	v_mbcnt_hi_u32_b32 v212, -1, v212
	v_bfe_u32 v212, v212, 4, 1
	v_mul_u32_u24_e32 v212, 24, v212
	v_mov_b32_e32 v213, 0
	v_readlane_b32 s4, v246, 57
	v_readlane_b32 s5, v246, 58
	v_readlane_b32 s6, v246, 59
	v_readlane_b32 s7, v246, 60
	v_readlane_b32 s8, v246, 61
	v_readlane_b32 s9, v246, 62
	v_readlane_b32 s10, v246, 63
	v_readlane_b32 s11, v245, 0
	v_readlane_b32 s12, v245, 1
	v_readlane_b32 s13, v245, 2
	v_readlane_b32 s14, v245, 3
	v_readlane_b32 s15, v245, 4
	v_lshlrev_b64 v[154:155], 1, v[156:157]
	v_mul_f32_e32 v151, v125, v125
	v_cvt_pk_bf16_f32 v152, v124, v125
	v_cvt_pk_bf16_f32 v153, v126, v127
	v_lshl_add_u64 v[156:157], s[20:21], 0, v[154:155]
	v_fmac_f32_e32 v151, v124, v124
	v_mov_b32_e32 v160, v152
	v_mov_b32_e32 v161, v153
	v_lshl_add_u64 v[164:165], v[156:157], 0, v[212:213]
	v_fmac_f32_e32 v151, v126, v126
	v_fmac_f32_e32 v151, v127, v127
	s_nop 0
	v_cvt_pk_bf16_f32 v124, v120, v121
	v_mul_f32_e32 v121, v121, v121
	v_or_b32_e32 v126, 32, v154
	v_mov_b32_e32 v127, v155
	v_fmac_f32_e32 v121, v120, v120
	v_cvt_pk_bf16_f32 v125, v122, v123
	v_lshl_add_u64 v[126:127], s[20:21], 0, v[126:127]
	v_fmac_f32_e32 v121, v122, v122
	v_mov_b32_e32 v162, v124
	v_mov_b32_e32 v163, v125
	s_nop 1
	v_permlane16_swap_b32_e32 v160, v162
	v_permlane16_swap_b32_e32 v161, v163
	ds_bpermute_b32 v160, v210, v160
	ds_bpermute_b32 v161, v210, v161
	ds_bpermute_b32 v162, v210, v162
	ds_bpermute_b32 v163, v210, v163
	ds_bpermute_b32 v164, v210, v164
	ds_bpermute_b32 v165, v210, v165
	s_waitcnt lgkmcnt(0)
	global_store_dwordx4 v[164:165], v[160:163], off
	v_fmac_f32_e32 v121, v123, v123
	v_add_f32_e32 v124, v151, v121
	s_nop 0
	v_cvt_pk_bf16_f32 v120, v116, v117
	v_mul_f32_e32 v117, v117, v117
	v_or_b32_e32 v122, 0x100, v154
	v_mov_b32_e32 v123, v155
	v_fmac_f32_e32 v117, v116, v116
	v_cvt_pk_bf16_f32 v121, v118, v119
	v_lshl_add_u64 v[122:123], s[20:21], 0, v[122:123]
	v_fmac_f32_e32 v117, v118, v118
	v_mov_b32_e32 v168, v120
	v_mov_b32_e32 v169, v121
	v_lshl_add_u64 v[166:167], v[122:123], 0, v[212:213]
	v_fmac_f32_e32 v117, v119, v119
	v_add_f32_e32 v120, v124, v117
	v_or_b32_e32 v154, 0x120, v154
	s_nop 0
	v_cvt_pk_bf16_f32 v116, v112, v113
	v_mul_f32_e32 v113, v113, v113
	v_fmac_f32_e32 v113, v112, v112
	v_fmac_f32_e32 v113, v114, v114
	v_fmac_f32_e32 v113, v115, v115
	v_add_f32_e32 v112, v120, v113
	ds_bpermute_b32 v113, v150, v112
	v_cvt_pk_bf16_f32 v117, v114, v115
	v_lshl_add_u64 v[118:119], s[20:21], 0, v[154:155]
	v_mov_b32_e32 v170, v116
	v_mov_b32_e32 v171, v117
	s_nop 1
	v_permlane16_swap_b32_e32 v168, v170
	v_permlane16_swap_b32_e32 v169, v171
	ds_bpermute_b32 v168, v210, v168
	ds_bpermute_b32 v169, v210, v169
	ds_bpermute_b32 v170, v210, v170
	ds_bpermute_b32 v171, v210, v171
	ds_bpermute_b32 v166, v210, v166
	ds_bpermute_b32 v167, v210, v167
	s_waitcnt lgkmcnt(0)
	global_store_dwordx4 v[166:167], v[168:171], off
	s_waitcnt lgkmcnt(0)
	v_add_f32_e32 v112, v112, v113
	ds_bpermute_b32 v113, v149, v112
	s_and_saveexec_b64 s[2:3], s[42:43]
	s_cbranch_execz .LBB0_673
	v_lshl_add_u64 v[114:115], v[144:145], 2, s[86:87]
	s_waitcnt lgkmcnt(0)
	v_add_f32_e32 v112, v112, v113
	global_atomic_add_f32 v[114:115], v112, off
; DI unsigned pk2(float a, float b) { f32x2 v = {a, b}; bf2_t r = __builtin_convertvector(v, bf2_t); return __builtin_bit_cast(unsigned, r); }
; __global__ void __launch_bounds__(512) hybrid_fwd(Params p) {
;     ...
;                   for (int m = 0; m < 4; ++m) { const int row = pm * 256 + ai * 128 + wr * 64 + m * 16 + fr; const size_t ro = (size_t)row * 1024 + pn * 256 + wc * 32 + 4 * fq;
;                       float ssq = 0.f;
; #pragma unroll
;                       for (int bj = 0; bj < 2; ++bj)
; #pragma unroll
;                           for (int n = 0; n < 2; ++n) { const size_t o = ro + bj * 128 + n * 16; const f32x4 v = *(const f32x4*)(X + o) + acc[ai][bj][m][n];
;                               u32x2 wv; wv[0] = pk2(v[0], v[1]); wv[1] = pk2(v[2], v[3]); *(u32x2*)(U + o) = wv;
;                               ssq += v[0] * v[0] + v[1] * v[1] + v[2] * v[2] + v[3] * v[3]; }
;                       ssq += __shfl_xor(ssq, 16); ssq += __shfl_xor(ssq, 32);
;                       if (fq == 0) unsafeAtomicAdd(SS1 + row, ssq); } }, vb); }
.LBB0_673:
	s_or_b64 exec, exec, s[2:3]
	v_or_b32_e32 v112, 16, v144
	s_waitcnt lgkmcnt(0)
	v_ashrrev_i32_e32 v113, 31, v112
	v_lshlrev_b64 v[114:115], 10, v[112:113]
	v_readlane_b32 s0, v246, 53
	v_lshl_add_u64 v[118:119], v[114:115], 0, v[142:143]
	v_readlane_b32 s1, v246, 54
	v_readlane_b32 s2, v246, 55
	v_readlane_b32 s3, v246, 56
	v_lshl_add_u64 v[120:121], v[118:119], 2, s[0:1]
	v_readlane_b32 s4, v246, 57
	v_readlane_b32 s5, v246, 58
	v_readlane_b32 s6, v246, 59
	v_readlane_b32 s7, v246, 60
	v_readlane_b32 s8, v246, 61
	v_readlane_b32 s9, v246, 62
	v_readlane_b32 s10, v246, 63
	v_readlane_b32 s11, v245, 0
	v_readlane_b32 s12, v245, 1
	v_readlane_b32 s13, v245, 2
	v_readlane_b32 s14, v245, 3
	v_readlane_b32 s15, v245, 4
	v_lshlrev_b64 v[116:117], 1, v[118:119]
	v_cvt_pk_bf16_f32 v114, v108, v109
	v_cvt_pk_bf16_f32 v115, v110, v111
	v_lshl_add_u64 v[118:119], s[20:21], 0, v[116:117]
	v_mov_b32_e32 v176, v114
	v_mov_b32_e32 v177, v115
	v_lshl_add_u64 v[184:185], v[118:119], 0, v[212:213]
	v_mul_f32_e32 v114, v109, v109
	v_fmac_f32_e32 v114, v108, v108
	v_fmac_f32_e32 v114, v110, v110
	v_fmac_f32_e32 v114, v111, v111
	s_nop 0
	v_cvt_pk_bf16_f32 v108, v104, v105
	v_mul_f32_e32 v105, v105, v105
	v_or_b32_e32 v110, 32, v116
	v_mov_b32_e32 v111, v117
	v_fmac_f32_e32 v105, v104, v104
	v_cvt_pk_bf16_f32 v109, v106, v107
	v_lshl_add_u64 v[110:111], s[20:21], 0, v[110:111]
	v_fmac_f32_e32 v105, v106, v106
	v_mov_b32_e32 v178, v108
	v_mov_b32_e32 v179, v109
	s_nop 1
	v_permlane16_swap_b32_e32 v176, v178
	v_permlane16_swap_b32_e32 v177, v179
	ds_bpermute_b32 v176, v210, v176
	ds_bpermute_b32 v177, v210, v177
	ds_bpermute_b32 v178, v210, v178
	ds_bpermute_b32 v179, v210, v179
	ds_bpermute_b32 v184, v210, v184
	ds_bpermute_b32 v185, v210, v185
	s_waitcnt lgkmcnt(0)
	global_store_dwordx4 v[184:185], v[176:179], off
	v_fmac_f32_e32 v105, v107, v107
	v_add_f32_e32 v108, v114, v105
	s_nop 0
	v_cvt_pk_bf16_f32 v104, v100, v101
	v_mul_f32_e32 v101, v101, v101
	v_or_b32_e32 v106, 0x100, v116
	v_mov_b32_e32 v107, v117
	v_fmac_f32_e32 v101, v100, v100
	v_cvt_pk_bf16_f32 v105, v102, v103
	v_lshl_add_u64 v[106:107], s[20:21], 0, v[106:107]
	v_fmac_f32_e32 v101, v102, v102
	v_mov_b32_e32 v180, v104
	v_mov_b32_e32 v181, v105
	v_lshl_add_u64 v[186:187], v[106:107], 0, v[212:213]
	v_fmac_f32_e32 v101, v103, v103
	v_add_f32_e32 v104, v108, v101
	v_or_b32_e32 v116, 0x120, v116
	s_nop 0
	v_cvt_pk_bf16_f32 v100, v96, v97
	v_mul_f32_e32 v97, v97, v97
	v_fmac_f32_e32 v97, v96, v96
	v_fmac_f32_e32 v97, v98, v98
	v_fmac_f32_e32 v97, v99, v99
	v_add_f32_e32 v96, v104, v97
	ds_bpermute_b32 v97, v150, v96
	v_cvt_pk_bf16_f32 v101, v98, v99
	v_lshl_add_u64 v[102:103], s[20:21], 0, v[116:117]
	v_mov_b32_e32 v182, v100
	v_mov_b32_e32 v183, v101
	s_nop 1
	v_permlane16_swap_b32_e32 v180, v182
	v_permlane16_swap_b32_e32 v181, v183
	ds_bpermute_b32 v180, v210, v180
	ds_bpermute_b32 v181, v210, v181
	ds_bpermute_b32 v182, v210, v182
	ds_bpermute_b32 v183, v210, v183
	ds_bpermute_b32 v186, v210, v186
	ds_bpermute_b32 v187, v210, v187
	s_waitcnt lgkmcnt(0)
	global_store_dwordx4 v[186:187], v[180:183], off
	s_waitcnt lgkmcnt(0)
	v_add_f32_e32 v96, v96, v97
	ds_bpermute_b32 v97, v149, v96
	s_and_saveexec_b64 s[2:3], s[42:43]
	s_cbranch_execz .LBB0_675
	v_lshl_add_u64 v[98:99], v[112:113], 2, s[86:87]
	s_waitcnt lgkmcnt(0)
	v_add_f32_e32 v96, v96, v97
	global_atomic_add_f32 v[98:99], v96, off
.LBB0_675:
	s_or_b64 exec, exec, s[2:3]
	v_or_b32_e32 v96, 32, v144
	s_waitcnt lgkmcnt(0)
	v_ashrrev_i32_e32 v97, 31, v96
	v_lshlrev_b64 v[98:99], 10, v[96:97]
	v_readlane_b32 s0, v246, 53
	v_lshl_add_u64 v[102:103], v[98:99], 0, v[142:143]
	v_readlane_b32 s1, v246, 54
	v_readlane_b32 s2, v246, 55
	v_readlane_b32 s3, v246, 56
	v_lshl_add_u64 v[104:105], v[102:103], 2, s[0:1]
	v_readlane_b32 s4, v246, 57
	v_readlane_b32 s5, v246, 58
	v_readlane_b32 s6, v246, 59
	v_readlane_b32 s7, v246, 60
	v_readlane_b32 s8, v246, 61
	v_readlane_b32 s9, v246, 62
	v_readlane_b32 s10, v246, 63
	v_readlane_b32 s11, v245, 0
	v_readlane_b32 s12, v245, 1
	v_readlane_b32 s13, v245, 2
	v_readlane_b32 s14, v245, 3
	v_readlane_b32 s15, v245, 4
	v_lshlrev_b64 v[100:101], 1, v[102:103]
	v_cvt_pk_bf16_f32 v98, v92, v93
	v_cvt_pk_bf16_f32 v99, v94, v95
	v_lshl_add_u64 v[102:103], s[20:21], 0, v[100:101]
	v_mov_b32_e32 v160, v98
	v_mov_b32_e32 v161, v99
	v_lshl_add_u64 v[164:165], v[102:103], 0, v[212:213]
	v_mul_f32_e32 v98, v93, v93
	v_fmac_f32_e32 v98, v92, v92
	v_fmac_f32_e32 v98, v94, v94
	v_fmac_f32_e32 v98, v95, v95
	s_nop 0
	v_cvt_pk_bf16_f32 v92, v88, v89
	v_mul_f32_e32 v89, v89, v89
	v_or_b32_e32 v94, 32, v100
	v_mov_b32_e32 v95, v101
	v_fmac_f32_e32 v89, v88, v88
	v_cvt_pk_bf16_f32 v93, v90, v91
	v_lshl_add_u64 v[94:95], s[20:21], 0, v[94:95]
	v_fmac_f32_e32 v89, v90, v90
	v_mov_b32_e32 v162, v92
	v_mov_b32_e32 v163, v93
	s_nop 1
	v_permlane16_swap_b32_e32 v160, v162
	v_permlane16_swap_b32_e32 v161, v163
	ds_bpermute_b32 v160, v210, v160
	ds_bpermute_b32 v161, v210, v161
	ds_bpermute_b32 v162, v210, v162
	ds_bpermute_b32 v163, v210, v163
	ds_bpermute_b32 v164, v210, v164
	ds_bpermute_b32 v165, v210, v165
	s_waitcnt lgkmcnt(0)
	global_store_dwordx4 v[164:165], v[160:163], off
	v_fmac_f32_e32 v89, v91, v91
	v_add_f32_e32 v92, v98, v89
	s_nop 0
	v_cvt_pk_bf16_f32 v88, v84, v85
	v_mul_f32_e32 v85, v85, v85
	v_or_b32_e32 v90, 0x100, v100
	v_mov_b32_e32 v91, v101
	v_fmac_f32_e32 v85, v84, v84
	v_cvt_pk_bf16_f32 v89, v86, v87
	v_lshl_add_u64 v[90:91], s[20:21], 0, v[90:91]
	v_fmac_f32_e32 v85, v86, v86
	v_mov_b32_e32 v168, v88
	v_mov_b32_e32 v169, v89
	v_lshl_add_u64 v[166:167], v[90:91], 0, v[212:213]
	v_fmac_f32_e32 v85, v87, v87
	v_add_f32_e32 v88, v92, v85
	v_or_b32_e32 v100, 0x120, v100
	s_nop 0
	v_cvt_pk_bf16_f32 v84, v80, v81
	v_mul_f32_e32 v81, v81, v81
	v_fmac_f32_e32 v81, v80, v80
	v_fmac_f32_e32 v81, v82, v82
	v_fmac_f32_e32 v81, v83, v83
	v_add_f32_e32 v80, v88, v81
	ds_bpermute_b32 v81, v150, v80
	v_cvt_pk_bf16_f32 v85, v82, v83
	v_lshl_add_u64 v[86:87], s[20:21], 0, v[100:101]
	v_mov_b32_e32 v170, v84
	v_mov_b32_e32 v171, v85
	s_nop 1
	v_permlane16_swap_b32_e32 v168, v170
	v_permlane16_swap_b32_e32 v169, v171
	ds_bpermute_b32 v168, v210, v168
	ds_bpermute_b32 v169, v210, v169
	ds_bpermute_b32 v170, v210, v170
	ds_bpermute_b32 v171, v210, v171
	ds_bpermute_b32 v166, v210, v166
	ds_bpermute_b32 v167, v210, v167
	s_waitcnt lgkmcnt(0)
	global_store_dwordx4 v[166:167], v[168:171], off
	s_waitcnt lgkmcnt(0)
	v_add_f32_e32 v80, v80, v81
	ds_bpermute_b32 v81, v149, v80
	s_and_saveexec_b64 s[2:3], s[42:43]
	s_cbranch_execz .LBB0_677
	v_lshl_add_u64 v[82:83], v[96:97], 2, s[86:87]
	s_waitcnt lgkmcnt(0)
	v_add_f32_e32 v80, v80, v81
	global_atomic_add_f32 v[82:83], v80, off
; DI unsigned pk2(float a, float b) { f32x2 v = {a, b}; bf2_t r = __builtin_convertvector(v, bf2_t); return __builtin_bit_cast(unsigned, r); }
; __global__ void __launch_bounds__(512) hybrid_fwd(Params p) {
;     ...
;                   for (int m = 0; m < 4; ++m) { const int row = pm * 256 + ai * 128 + wr * 64 + m * 16 + fr; const size_t ro = (size_t)row * 1024 + pn * 256 + wc * 32 + 4 * fq;
;                       float ssq = 0.f;
; #pragma unroll
;                       for (int bj = 0; bj < 2; ++bj)
; #pragma unroll
;                           for (int n = 0; n < 2; ++n) { const size_t o = ro + bj * 128 + n * 16; const f32x4 v = *(const f32x4*)(X + o) + acc[ai][bj][m][n];
;                               u32x2 wv; wv[0] = pk2(v[0], v[1]); wv[1] = pk2(v[2], v[3]); *(u32x2*)(U + o) = wv;
;                               ssq += v[0] * v[0] + v[1] * v[1] + v[2] * v[2] + v[3] * v[3]; }
;                       ssq += __shfl_xor(ssq, 16); ssq += __shfl_xor(ssq, 32);
;                       if (fq == 0) unsafeAtomicAdd(SS1 + row, ssq); } }, vb); }
.LBB0_677:
	s_or_b64 exec, exec, s[2:3]
	v_or_b32_e32 v80, 48, v144
	s_waitcnt lgkmcnt(0)
	v_ashrrev_i32_e32 v81, 31, v80
	v_lshlrev_b64 v[82:83], 10, v[80:81]
	v_readlane_b32 s0, v246, 53
	v_lshl_add_u64 v[86:87], v[82:83], 0, v[142:143]
	v_readlane_b32 s1, v246, 54
	v_readlane_b32 s2, v246, 55
	v_readlane_b32 s3, v246, 56
	v_lshl_add_u64 v[88:89], v[86:87], 2, s[0:1]
	v_readlane_b32 s4, v246, 57
	v_readlane_b32 s5, v246, 58
	v_readlane_b32 s6, v246, 59
	v_readlane_b32 s7, v246, 60
	v_readlane_b32 s8, v246, 61
	v_readlane_b32 s9, v246, 62
	v_readlane_b32 s10, v246, 63
	v_readlane_b32 s11, v245, 0
	v_readlane_b32 s12, v245, 1
	v_readlane_b32 s13, v245, 2
	v_readlane_b32 s14, v245, 3
	v_readlane_b32 s15, v245, 4
	v_lshlrev_b64 v[84:85], 1, v[86:87]
	v_cvt_pk_bf16_f32 v82, v76, v77
	v_cvt_pk_bf16_f32 v83, v78, v79
	v_lshl_add_u64 v[86:87], s[20:21], 0, v[84:85]
	v_mov_b32_e32 v176, v82
	v_mov_b32_e32 v177, v83
	v_lshl_add_u64 v[184:185], v[86:87], 0, v[212:213]
	v_mul_f32_e32 v82, v77, v77
	v_fmac_f32_e32 v82, v76, v76
	v_fmac_f32_e32 v82, v78, v78
	v_fmac_f32_e32 v82, v79, v79
	s_nop 0
	v_cvt_pk_bf16_f32 v76, v72, v73
	v_mul_f32_e32 v73, v73, v73
	v_or_b32_e32 v78, 32, v84
	v_mov_b32_e32 v79, v85
	v_fmac_f32_e32 v73, v72, v72
	v_cvt_pk_bf16_f32 v77, v74, v75
	v_lshl_add_u64 v[78:79], s[20:21], 0, v[78:79]
	v_fmac_f32_e32 v73, v74, v74
	v_mov_b32_e32 v178, v76
	v_mov_b32_e32 v179, v77
	s_nop 1
	v_permlane16_swap_b32_e32 v176, v178
	v_permlane16_swap_b32_e32 v177, v179
	ds_bpermute_b32 v176, v210, v176
	ds_bpermute_b32 v177, v210, v177
	ds_bpermute_b32 v178, v210, v178
	ds_bpermute_b32 v179, v210, v179
	ds_bpermute_b32 v184, v210, v184
	ds_bpermute_b32 v185, v210, v185
	s_waitcnt lgkmcnt(0)
	global_store_dwordx4 v[184:185], v[176:179], off
	v_fmac_f32_e32 v73, v75, v75
	v_add_f32_e32 v76, v82, v73
	s_nop 0
	v_cvt_pk_bf16_f32 v72, v68, v69
	v_mul_f32_e32 v69, v69, v69
	v_or_b32_e32 v74, 0x100, v84
	v_mov_b32_e32 v75, v85
	v_fmac_f32_e32 v69, v68, v68
	v_cvt_pk_bf16_f32 v73, v70, v71
	v_lshl_add_u64 v[74:75], s[20:21], 0, v[74:75]
	v_fmac_f32_e32 v69, v70, v70
	v_mov_b32_e32 v180, v72
	v_mov_b32_e32 v181, v73
	v_lshl_add_u64 v[186:187], v[74:75], 0, v[212:213]
	v_fmac_f32_e32 v69, v71, v71
	v_add_f32_e32 v72, v76, v69
	v_or_b32_e32 v84, 0x120, v84
	s_nop 0
	v_cvt_pk_bf16_f32 v68, v64, v65
	v_mul_f32_e32 v65, v65, v65
	v_fmac_f32_e32 v65, v64, v64
	v_fmac_f32_e32 v65, v66, v66
	v_fmac_f32_e32 v65, v67, v67
	v_add_f32_e32 v64, v72, v65
	ds_bpermute_b32 v65, v150, v64
	v_cvt_pk_bf16_f32 v69, v66, v67
	v_lshl_add_u64 v[70:71], s[20:21], 0, v[84:85]
	v_mov_b32_e32 v182, v68
	v_mov_b32_e32 v183, v69
	s_nop 1
	v_permlane16_swap_b32_e32 v180, v182
	v_permlane16_swap_b32_e32 v181, v183
	ds_bpermute_b32 v180, v210, v180
	ds_bpermute_b32 v181, v210, v181
	ds_bpermute_b32 v182, v210, v182
	ds_bpermute_b32 v183, v210, v183
	ds_bpermute_b32 v186, v210, v186
	ds_bpermute_b32 v187, v210, v187
	s_waitcnt lgkmcnt(0)
	global_store_dwordx4 v[186:187], v[180:183], off
	s_waitcnt lgkmcnt(0)
	v_add_f32_e32 v64, v64, v65
	ds_bpermute_b32 v65, v149, v64
	s_and_saveexec_b64 s[2:3], s[42:43]
	s_cbranch_execz .LBB0_679
	v_lshl_add_u64 v[66:67], v[80:81], 2, s[86:87]
	s_waitcnt lgkmcnt(0)
	v_add_f32_e32 v64, v64, v65
	global_atomic_add_f32 v[66:67], v64, off
.LBB0_679:
	s_or_b64 exec, exec, s[2:3]
	v_add_u32_e32 v64, 0x80, v144
	s_waitcnt lgkmcnt(0)
	v_ashrrev_i32_e32 v65, 31, v64
	v_lshlrev_b64 v[66:67], 10, v[64:65]
	v_readlane_b32 s0, v246, 53
	v_lshl_add_u64 v[70:71], v[66:67], 0, v[142:143]
	v_readlane_b32 s1, v246, 54
	v_readlane_b32 s2, v246, 55
	v_readlane_b32 s3, v246, 56
	v_lshl_add_u64 v[72:73], v[70:71], 2, s[0:1]
	v_readlane_b32 s4, v246, 57
	v_readlane_b32 s5, v246, 58
	v_readlane_b32 s6, v246, 59
	v_readlane_b32 s7, v246, 60
	v_readlane_b32 s8, v246, 61
	v_readlane_b32 s9, v246, 62
	v_readlane_b32 s10, v246, 63
	v_readlane_b32 s11, v245, 0
	v_readlane_b32 s12, v245, 1
	v_readlane_b32 s13, v245, 2
	v_readlane_b32 s14, v245, 3
	v_readlane_b32 s15, v245, 4
	v_lshlrev_b64 v[68:69], 1, v[70:71]
	v_cvt_pk_bf16_f32 v66, v60, v61
	v_cvt_pk_bf16_f32 v67, v62, v63
	v_lshl_add_u64 v[70:71], s[20:21], 0, v[68:69]
	v_mov_b32_e32 v160, v66
	v_mov_b32_e32 v161, v67
	v_lshl_add_u64 v[164:165], v[70:71], 0, v[212:213]
	v_mul_f32_e32 v66, v61, v61
	v_fmac_f32_e32 v66, v60, v60
	v_fmac_f32_e32 v66, v62, v62
	v_fmac_f32_e32 v66, v63, v63
	s_nop 0
	v_cvt_pk_bf16_f32 v60, v56, v57
	v_mul_f32_e32 v57, v57, v57
	v_or_b32_e32 v62, 32, v68
	v_mov_b32_e32 v63, v69
	v_fmac_f32_e32 v57, v56, v56
	v_cvt_pk_bf16_f32 v61, v58, v59
	v_lshl_add_u64 v[62:63], s[20:21], 0, v[62:63]
	v_fmac_f32_e32 v57, v58, v58
	v_mov_b32_e32 v162, v60
	v_mov_b32_e32 v163, v61
	s_nop 1
	v_permlane16_swap_b32_e32 v160, v162
	v_permlane16_swap_b32_e32 v161, v163
	ds_bpermute_b32 v160, v210, v160
	ds_bpermute_b32 v161, v210, v161
	ds_bpermute_b32 v162, v210, v162
	ds_bpermute_b32 v163, v210, v163
	ds_bpermute_b32 v164, v210, v164
	ds_bpermute_b32 v165, v210, v165
	s_waitcnt lgkmcnt(0)
	global_store_dwordx4 v[164:165], v[160:163], off
	v_fmac_f32_e32 v57, v59, v59
	v_add_f32_e32 v60, v66, v57
	s_nop 0
	v_cvt_pk_bf16_f32 v56, v52, v53
	v_mul_f32_e32 v53, v53, v53
	v_or_b32_e32 v58, 0x100, v68
	v_mov_b32_e32 v59, v69
	v_fmac_f32_e32 v53, v52, v52
	v_cvt_pk_bf16_f32 v57, v54, v55
	v_lshl_add_u64 v[58:59], s[20:21], 0, v[58:59]
	v_fmac_f32_e32 v53, v54, v54
	v_mov_b32_e32 v168, v56
	v_mov_b32_e32 v169, v57
	v_lshl_add_u64 v[166:167], v[58:59], 0, v[212:213]
	v_fmac_f32_e32 v53, v55, v55
	v_add_f32_e32 v56, v60, v53
	v_or_b32_e32 v68, 0x120, v68
	s_nop 0
	v_cvt_pk_bf16_f32 v52, v48, v49
	v_mul_f32_e32 v49, v49, v49
	v_fmac_f32_e32 v49, v48, v48
	v_fmac_f32_e32 v49, v50, v50
	v_fmac_f32_e32 v49, v51, v51
	v_add_f32_e32 v48, v56, v49
	ds_bpermute_b32 v49, v150, v48
	v_cvt_pk_bf16_f32 v53, v50, v51
	v_lshl_add_u64 v[54:55], s[20:21], 0, v[68:69]
	v_mov_b32_e32 v170, v52
	v_mov_b32_e32 v171, v53
	s_nop 1
	v_permlane16_swap_b32_e32 v168, v170
	v_permlane16_swap_b32_e32 v169, v171
	ds_bpermute_b32 v168, v210, v168
	ds_bpermute_b32 v169, v210, v169
	ds_bpermute_b32 v170, v210, v170
	ds_bpermute_b32 v171, v210, v171
	ds_bpermute_b32 v166, v210, v166
	ds_bpermute_b32 v167, v210, v167
	s_waitcnt lgkmcnt(0)
	global_store_dwordx4 v[166:167], v[168:171], off
	s_waitcnt lgkmcnt(0)
	v_add_f32_e32 v48, v48, v49
	ds_bpermute_b32 v49, v149, v48
	s_and_saveexec_b64 s[2:3], s[42:43]
	s_cbranch_execz .LBB0_681
	v_lshl_add_u64 v[50:51], v[64:65], 2, s[86:87]
	s_waitcnt lgkmcnt(0)
	v_add_f32_e32 v48, v48, v49
	global_atomic_add_f32 v[50:51], v48, off
; DI unsigned pk2(float a, float b) { f32x2 v = {a, b}; bf2_t r = __builtin_convertvector(v, bf2_t); return __builtin_bit_cast(unsigned, r); }
; __global__ void __launch_bounds__(512) hybrid_fwd(Params p) {
;     ...
;                   for (int m = 0; m < 4; ++m) { const int row = pm * 256 + ai * 128 + wr * 64 + m * 16 + fr; const size_t ro = (size_t)row * 1024 + pn * 256 + wc * 32 + 4 * fq;
;                       float ssq = 0.f;
; #pragma unroll
;                       for (int bj = 0; bj < 2; ++bj)
; #pragma unroll
;                           for (int n = 0; n < 2; ++n) { const size_t o = ro + bj * 128 + n * 16; const f32x4 v = *(const f32x4*)(X + o) + acc[ai][bj][m][n];
;                               u32x2 wv; wv[0] = pk2(v[0], v[1]); wv[1] = pk2(v[2], v[3]); *(u32x2*)(U + o) = wv;
;                               ssq += v[0] * v[0] + v[1] * v[1] + v[2] * v[2] + v[3] * v[3]; }
;                       ssq += __shfl_xor(ssq, 16); ssq += __shfl_xor(ssq, 32);
;                       if (fq == 0) unsafeAtomicAdd(SS1 + row, ssq); } }, vb); }
.LBB0_681:
	s_or_b64 exec, exec, s[2:3]
	v_add_u32_e32 v48, 0x90, v144
	s_waitcnt lgkmcnt(0)
	v_ashrrev_i32_e32 v49, 31, v48
	v_lshlrev_b64 v[50:51], 10, v[48:49]
	v_readlane_b32 s0, v246, 53
	v_lshl_add_u64 v[54:55], v[50:51], 0, v[142:143]
	v_readlane_b32 s1, v246, 54
	v_readlane_b32 s2, v246, 55
	v_readlane_b32 s3, v246, 56
	v_lshl_add_u64 v[56:57], v[54:55], 2, s[0:1]
	v_readlane_b32 s4, v246, 57
	v_readlane_b32 s5, v246, 58
	v_readlane_b32 s6, v246, 59
	v_readlane_b32 s7, v246, 60
	v_readlane_b32 s8, v246, 61
	v_readlane_b32 s9, v246, 62
	v_readlane_b32 s10, v246, 63
	v_readlane_b32 s11, v245, 0
	v_readlane_b32 s12, v245, 1
	v_readlane_b32 s13, v245, 2
	v_readlane_b32 s14, v245, 3
	v_readlane_b32 s15, v245, 4
	v_lshlrev_b64 v[52:53], 1, v[54:55]
	v_cvt_pk_bf16_f32 v50, v44, v45
	v_cvt_pk_bf16_f32 v51, v46, v47
	v_lshl_add_u64 v[54:55], s[20:21], 0, v[52:53]
	v_mov_b32_e32 v176, v50
	v_mov_b32_e32 v177, v51
	v_lshl_add_u64 v[184:185], v[54:55], 0, v[212:213]
	v_mul_f32_e32 v50, v45, v45
	v_fmac_f32_e32 v50, v44, v44
	v_fmac_f32_e32 v50, v46, v46
	v_fmac_f32_e32 v50, v47, v47
	s_nop 0
	v_cvt_pk_bf16_f32 v44, v40, v41
	v_mul_f32_e32 v41, v41, v41
	v_or_b32_e32 v46, 32, v52
	v_mov_b32_e32 v47, v53
	v_fmac_f32_e32 v41, v40, v40
	v_cvt_pk_bf16_f32 v45, v42, v43
	v_lshl_add_u64 v[46:47], s[20:21], 0, v[46:47]
	v_fmac_f32_e32 v41, v42, v42
	v_mov_b32_e32 v178, v44
	v_mov_b32_e32 v179, v45
	s_nop 1
	v_permlane16_swap_b32_e32 v176, v178
	v_permlane16_swap_b32_e32 v177, v179
	ds_bpermute_b32 v176, v210, v176
	ds_bpermute_b32 v177, v210, v177
	ds_bpermute_b32 v178, v210, v178
	ds_bpermute_b32 v179, v210, v179
	ds_bpermute_b32 v184, v210, v184
	ds_bpermute_b32 v185, v210, v185
	s_waitcnt lgkmcnt(0)
	global_store_dwordx4 v[184:185], v[176:179], off
	v_fmac_f32_e32 v41, v43, v43
	v_add_f32_e32 v44, v50, v41
	s_nop 0
	v_cvt_pk_bf16_f32 v40, v36, v37
	v_mul_f32_e32 v37, v37, v37
	v_or_b32_e32 v42, 0x100, v52
	v_mov_b32_e32 v43, v53
	v_fmac_f32_e32 v37, v36, v36
	v_cvt_pk_bf16_f32 v41, v38, v39
	v_lshl_add_u64 v[42:43], s[20:21], 0, v[42:43]
	v_fmac_f32_e32 v37, v38, v38
	v_mov_b32_e32 v180, v40
	v_mov_b32_e32 v181, v41
	v_lshl_add_u64 v[186:187], v[42:43], 0, v[212:213]
	v_fmac_f32_e32 v37, v39, v39
	v_add_f32_e32 v40, v44, v37
	v_or_b32_e32 v52, 0x120, v52
	s_nop 0
	v_cvt_pk_bf16_f32 v36, v32, v33
	v_mul_f32_e32 v33, v33, v33
	v_fmac_f32_e32 v33, v32, v32
	v_fmac_f32_e32 v33, v34, v34
	v_fmac_f32_e32 v33, v35, v35
	v_add_f32_e32 v32, v40, v33
	ds_bpermute_b32 v33, v150, v32
	v_cvt_pk_bf16_f32 v37, v34, v35
	v_lshl_add_u64 v[38:39], s[20:21], 0, v[52:53]
	v_mov_b32_e32 v182, v36
	v_mov_b32_e32 v183, v37
	s_nop 1
	v_permlane16_swap_b32_e32 v180, v182
	v_permlane16_swap_b32_e32 v181, v183
	ds_bpermute_b32 v180, v210, v180
	ds_bpermute_b32 v181, v210, v181
	ds_bpermute_b32 v182, v210, v182
	ds_bpermute_b32 v183, v210, v183
	ds_bpermute_b32 v186, v210, v186
	ds_bpermute_b32 v187, v210, v187
	s_waitcnt lgkmcnt(0)
	global_store_dwordx4 v[186:187], v[180:183], off
	s_waitcnt lgkmcnt(0)
	v_add_f32_e32 v32, v32, v33
	ds_bpermute_b32 v33, v149, v32
	s_and_saveexec_b64 s[2:3], s[42:43]
	s_cbranch_execz .LBB0_683
	v_lshl_add_u64 v[34:35], v[48:49], 2, s[86:87]
	s_waitcnt lgkmcnt(0)
	v_add_f32_e32 v32, v32, v33
	global_atomic_add_f32 v[34:35], v32, off
; DI unsigned pk2(float a, float b) { f32x2 v = {a, b}; bf2_t r = __builtin_convertvector(v, bf2_t); return __builtin_bit_cast(unsigned, r); }
; __global__ void __launch_bounds__(512) hybrid_fwd(Params p) {
;     ...
;                   for (int m = 0; m < 4; ++m) { const int row = pm * 256 + ai * 128 + wr * 64 + m * 16 + fr; const size_t ro = (size_t)row * 1024 + pn * 256 + wc * 32 + 4 * fq;
;                       float ssq = 0.f;
; #pragma unroll
;                       for (int bj = 0; bj < 2; ++bj)
; #pragma unroll
;                           for (int n = 0; n < 2; ++n) { const size_t o = ro + bj * 128 + n * 16; const f32x4 v = *(const f32x4*)(X + o) + acc[ai][bj][m][n];
;                               u32x2 wv; wv[0] = pk2(v[0], v[1]); wv[1] = pk2(v[2], v[3]); *(u32x2*)(U + o) = wv;
;                               ssq += v[0] * v[0] + v[1] * v[1] + v[2] * v[2] + v[3] * v[3]; }
;                       ssq += __shfl_xor(ssq, 16); ssq += __shfl_xor(ssq, 32);
;                       if (fq == 0) unsafeAtomicAdd(SS1 + row, ssq); } }, vb); }
.LBB0_683:
	s_or_b64 exec, exec, s[2:3]
	v_add_u32_e32 v32, 0xa0, v144
	s_waitcnt lgkmcnt(0)
	v_ashrrev_i32_e32 v33, 31, v32
	v_lshlrev_b64 v[34:35], 10, v[32:33]
	v_readlane_b32 s0, v246, 53
	v_lshl_add_u64 v[38:39], v[34:35], 0, v[142:143]
	v_readlane_b32 s1, v246, 54
	v_readlane_b32 s2, v246, 55
	v_readlane_b32 s3, v246, 56
	v_lshl_add_u64 v[40:41], v[38:39], 2, s[0:1]
	v_readlane_b32 s4, v246, 57
	v_readlane_b32 s5, v246, 58
	v_readlane_b32 s6, v246, 59
	v_readlane_b32 s7, v246, 60
	v_readlane_b32 s8, v246, 61
	v_readlane_b32 s9, v246, 62
	v_readlane_b32 s10, v246, 63
	v_readlane_b32 s11, v245, 0
	v_readlane_b32 s12, v245, 1
	v_readlane_b32 s13, v245, 2
	v_readlane_b32 s14, v245, 3
	v_readlane_b32 s15, v245, 4
	v_lshlrev_b64 v[36:37], 1, v[38:39]
	v_cvt_pk_bf16_f32 v34, v28, v29
	v_cvt_pk_bf16_f32 v35, v30, v31
	v_lshl_add_u64 v[38:39], s[20:21], 0, v[36:37]
	v_mov_b32_e32 v160, v34
	v_mov_b32_e32 v161, v35
	v_lshl_add_u64 v[164:165], v[38:39], 0, v[212:213]
	v_mul_f32_e32 v34, v29, v29
	v_fmac_f32_e32 v34, v28, v28
	v_fmac_f32_e32 v34, v30, v30
	v_fmac_f32_e32 v34, v31, v31
	s_nop 0
	v_cvt_pk_bf16_f32 v28, v24, v25
	v_mul_f32_e32 v25, v25, v25
	v_or_b32_e32 v30, 32, v36
	v_mov_b32_e32 v31, v37
	v_fmac_f32_e32 v25, v24, v24
	v_cvt_pk_bf16_f32 v29, v26, v27
	v_lshl_add_u64 v[30:31], s[20:21], 0, v[30:31]
	v_fmac_f32_e32 v25, v26, v26
	v_mov_b32_e32 v162, v28
	v_mov_b32_e32 v163, v29
	s_nop 1
	v_permlane16_swap_b32_e32 v160, v162
	v_permlane16_swap_b32_e32 v161, v163
	ds_bpermute_b32 v160, v210, v160
	ds_bpermute_b32 v161, v210, v161
	ds_bpermute_b32 v162, v210, v162
	ds_bpermute_b32 v163, v210, v163
	ds_bpermute_b32 v164, v210, v164
	ds_bpermute_b32 v165, v210, v165
	s_waitcnt lgkmcnt(0)
	global_store_dwordx4 v[164:165], v[160:163], off
	v_fmac_f32_e32 v25, v27, v27
	v_add_f32_e32 v28, v34, v25
	s_nop 0
	v_cvt_pk_bf16_f32 v24, v20, v21
	v_mul_f32_e32 v21, v21, v21
	v_or_b32_e32 v26, 0x100, v36
	v_mov_b32_e32 v27, v37
	v_fmac_f32_e32 v21, v20, v20
	v_cvt_pk_bf16_f32 v25, v22, v23
	v_lshl_add_u64 v[26:27], s[20:21], 0, v[26:27]
	v_fmac_f32_e32 v21, v22, v22
	v_mov_b32_e32 v168, v24
	v_mov_b32_e32 v169, v25
	v_lshl_add_u64 v[166:167], v[26:27], 0, v[212:213]
	v_fmac_f32_e32 v21, v23, v23
	v_add_f32_e32 v24, v28, v21
	v_or_b32_e32 v36, 0x120, v36
	s_nop 0
	v_cvt_pk_bf16_f32 v20, v16, v17
	v_mul_f32_e32 v17, v17, v17
	v_fmac_f32_e32 v17, v16, v16
	v_fmac_f32_e32 v17, v18, v18
	v_fmac_f32_e32 v17, v19, v19
	v_add_f32_e32 v16, v24, v17
	ds_bpermute_b32 v17, v150, v16
	v_cvt_pk_bf16_f32 v21, v18, v19
	v_lshl_add_u64 v[22:23], s[20:21], 0, v[36:37]
	v_mov_b32_e32 v170, v20
	v_mov_b32_e32 v171, v21
	s_nop 1
	v_permlane16_swap_b32_e32 v168, v170
	v_permlane16_swap_b32_e32 v169, v171
	ds_bpermute_b32 v168, v210, v168
	ds_bpermute_b32 v169, v210, v169
	ds_bpermute_b32 v170, v210, v170
	ds_bpermute_b32 v171, v210, v171
	ds_bpermute_b32 v166, v210, v166
	ds_bpermute_b32 v167, v210, v167
	s_waitcnt lgkmcnt(0)
	global_store_dwordx4 v[166:167], v[168:171], off
	s_waitcnt lgkmcnt(0)
	v_add_f32_e32 v16, v16, v17
	ds_bpermute_b32 v17, v149, v16
	s_and_saveexec_b64 s[2:3], s[42:43]
	s_cbranch_execz .LBB0_685
	v_lshl_add_u64 v[18:19], v[32:33], 2, s[86:87]
	s_waitcnt lgkmcnt(0)
	v_add_f32_e32 v16, v16, v17
	global_atomic_add_f32 v[18:19], v16, off
.LBB0_685:
	s_or_b64 exec, exec, s[2:3]
	v_add_u32_e32 v16, 0xb0, v144
	s_waitcnt lgkmcnt(0)
	v_ashrrev_i32_e32 v17, 31, v16
	v_lshlrev_b64 v[18:19], 10, v[16:17]
	v_readlane_b32 s0, v246, 53
	v_lshl_add_u64 v[22:23], v[18:19], 0, v[142:143]
	v_readlane_b32 s1, v246, 54
	v_readlane_b32 s2, v246, 55
	v_readlane_b32 s3, v246, 56
	v_lshl_add_u64 v[24:25], v[22:23], 2, s[0:1]
	v_readlane_b32 s4, v246, 57
	v_readlane_b32 s5, v246, 58
	v_readlane_b32 s6, v246, 59
	v_readlane_b32 s7, v246, 60
	v_readlane_b32 s8, v246, 61
	v_readlane_b32 s9, v246, 62
	v_readlane_b32 s10, v246, 63
	v_readlane_b32 s11, v245, 0
	v_readlane_b32 s12, v245, 1
	v_readlane_b32 s13, v245, 2
	v_readlane_b32 s14, v245, 3
	v_readlane_b32 s15, v245, 4
	v_lshlrev_b64 v[20:21], 1, v[22:23]
	v_cvt_pk_bf16_f32 v18, v12, v13
	v_cvt_pk_bf16_f32 v19, v14, v15
	v_lshl_add_u64 v[22:23], s[20:21], 0, v[20:21]
	v_mov_b32_e32 v176, v18
	v_mov_b32_e32 v177, v19
	v_lshl_add_u64 v[184:185], v[22:23], 0, v[212:213]
	v_mul_f32_e32 v18, v13, v13
	v_fmac_f32_e32 v18, v12, v12
	v_fmac_f32_e32 v18, v14, v14
	v_fmac_f32_e32 v18, v15, v15
	s_nop 0
	v_cvt_pk_bf16_f32 v12, v8, v9
	v_mul_f32_e32 v9, v9, v9
	v_or_b32_e32 v14, 32, v20
	v_mov_b32_e32 v15, v21
	v_fmac_f32_e32 v9, v8, v8
	v_cvt_pk_bf16_f32 v13, v10, v11
	v_lshl_add_u64 v[14:15], s[20:21], 0, v[14:15]
	v_fmac_f32_e32 v9, v10, v10
	v_mov_b32_e32 v178, v12
	v_mov_b32_e32 v179, v13
	s_nop 1
	v_permlane16_swap_b32_e32 v176, v178
	v_permlane16_swap_b32_e32 v177, v179
	ds_bpermute_b32 v176, v210, v176
	ds_bpermute_b32 v177, v210, v177
	ds_bpermute_b32 v178, v210, v178
	ds_bpermute_b32 v179, v210, v179
	ds_bpermute_b32 v184, v210, v184
	ds_bpermute_b32 v185, v210, v185
	s_waitcnt lgkmcnt(0)
	global_store_dwordx4 v[184:185], v[176:179], off
	v_fmac_f32_e32 v9, v11, v11
	v_add_f32_e32 v12, v18, v9
	s_nop 0
	v_cvt_pk_bf16_f32 v8, v4, v5
	v_mul_f32_e32 v5, v5, v5
	v_or_b32_e32 v10, 0x100, v20
	v_mov_b32_e32 v11, v21
	v_fmac_f32_e32 v5, v4, v4
	v_cvt_pk_bf16_f32 v9, v6, v7
	v_lshl_add_u64 v[10:11], s[20:21], 0, v[10:11]
	v_fmac_f32_e32 v5, v6, v6
	v_mov_b32_e32 v180, v8
	v_mov_b32_e32 v181, v9
	v_lshl_add_u64 v[186:187], v[10:11], 0, v[212:213]
	v_fmac_f32_e32 v5, v7, v7
	v_add_f32_e32 v8, v12, v5
	v_or_b32_e32 v20, 0x120, v20
	s_nop 0
	v_cvt_pk_bf16_f32 v4, v0, v1
	v_mul_f32_e32 v1, v1, v1
	v_fmac_f32_e32 v1, v0, v0
	v_fmac_f32_e32 v1, v2, v2
	v_fmac_f32_e32 v1, v3, v3
	v_add_f32_e32 v0, v8, v1
	ds_bpermute_b32 v1, v150, v0
	v_cvt_pk_bf16_f32 v5, v2, v3
	v_lshl_add_u64 v[6:7], s[20:21], 0, v[20:21]
	v_mov_b32_e32 v182, v4
	v_mov_b32_e32 v183, v5
	s_nop 1
	v_permlane16_swap_b32_e32 v180, v182
	v_permlane16_swap_b32_e32 v181, v183
	ds_bpermute_b32 v180, v210, v180
	ds_bpermute_b32 v181, v210, v181
	ds_bpermute_b32 v182, v210, v182
	ds_bpermute_b32 v183, v210, v183
	ds_bpermute_b32 v186, v210, v186
	ds_bpermute_b32 v187, v210, v187
	s_waitcnt lgkmcnt(0)
	global_store_dwordx4 v[186:187], v[180:183], off
	s_waitcnt lgkmcnt(0)
	v_add_f32_e32 v0, v0, v1
	ds_bpermute_b32 v1, v149, v0
	s_and_saveexec_b64 s[2:3], s[42:43]
	s_cbranch_execz .LBB0_666
	v_lshl_add_u64 v[2:3], v[16:17], 2, s[86:87]
	s_waitcnt lgkmcnt(0)
	v_add_f32_e32 v0, v0, v1
	global_atomic_add_f32 v[2:3], v0, off
	s_branch .LBB0_666

; #define G_STAGE(bufoff, gbase, voff) do { _Pragma("unroll") for (int _i = 0; _i < 2; ++_i) \
;         __builtin_amdgcn_global_load_lds((const unsigned*)((const char*)(gbase) + (voff)[_i]), (LAS unsigned*)(lds + (bufoff) + ldsw + _i * 8192), 16, 0, 0); } while (0)
; #define G_LDA(dst, b, h) do { _Pragma("unroll") for (int m = 0; m < 4; ++m) _Pragma("unroll") for (int k = 0; k < 2; ++k) dst[m][k] = *(const LAS bf16x8*)(lds + G_SA(b, h) + aoff + m * 2048 + k * 1024); } while (0)
; #define G_WAIT_V(n) asm volatile("s_waitcnt vmcnt(" #n ")" ::: "memory")
; #define G_WAIT_L(n) asm volatile("s_waitcnt lgkmcnt(" #n ")" ::: "memory")
; #define G_BAR __builtin_amdgcn_s_barrier()
; template <bool PERM, class Dec, class Epi>
; DI void gemm_phase(LAS unsigned char* lds, const int nM, const int nN, const int K, const int lda, const int ldb, const Dec& dec, const Epi& epi, const int vb, const int panel = -1) {
;     ...
;         for (int t = 0; t < nt; t += 2) {
;             const bool last = (t == nt - 2);
;             const char* a1 = cA + (size_t)(t + 1) * kstep;
;             const char* a2 = last ? nA : cA + (size_t)(t + 2) * kstep; const char* b2 = last ? nB : cB + (size_t)(t + 2) * kstep;
;             const char* a3 = a2 + kstep; const char* b3 = b2 + kstep;
;             G_LDB(B0, 0, 0); G_SCHED; G_LDA(At, 0, 0); G_STAGE(G_SA(1, 1), a1 + hstepA, voffA);
;             G_WAIT_L(8); G_BAR; G_WAIT_L(0); G_MMA(0, 0, At, B0); G_BAR; G_SCHED;
;             G_LDB(B1, 0, 1); G_STAGE(G_SB(0, 0), b2, voffB);
;             G_BAR; G_WAIT_L(0); G_MMA(0, 1, At, B1); G_BAR;
;             G_LDA(At, 0, 1); G_STAGE(G_SA(0, 0), a2, voffA);
;             G_BAR; G_WAIT_L(0); G_MMA(1, 0, At, B0); G_BAR; G_SCHED;
;             G_STAGE(G_SB(0, 1), b2 + hstepB, voffB);
;             G_WAIT_V(6); G_BAR; G_MMA(1, 1, At, B1); G_BAR;
;             G_LDB(B0, 1, 0); G_SCHED; G_LDA(At, 1, 0); G_STAGE(G_SA(0, 1), a2 + hstepA, voffA);
;             G_WAIT_L(8); G_BAR; G_WAIT_L(0); G_MMA(0, 0, At, B0); G_BAR; G_SCHED;
;             G_LDB(B1, 1, 1); G_STAGE(G_SB(1, 0), b3, voffB);
;             G_BAR; G_WAIT_L(0); G_MMA(0, 1, At, B1); G_BAR;
;             G_LDA(At, 1, 1); G_STAGE(G_SA(1, 0), a3, voffA);
;             G_BAR; G_WAIT_L(0); G_MMA(1, 0, At, B0); G_BAR; G_SCHED;
;             G_STAGE(G_SB(1, 1), b3 + hstepB, voffB);
;             G_WAIT_V(6); G_BAR; G_MMA(1, 1, At, B1); G_BAR;
;         }
.LBB0_924:
	s_add_u32 s22, s18, 0x100
	s_addc_u32 s23, s19, 0
	s_add_i32 s53, 0, 0x10000
	v_add_u32_e32 v140, s53, v144
	ds_read_b128 v[162:165], v140
	ds_read_b128 v[166:169], v140 offset:1024
	ds_read_b128 v[170:173], v140 offset:2048
	ds_read_b128 v[176:179], v140 offset:3072
	s_cmp_eq_u32 s52, 20
	s_cselect_b32 s29, s13, s23
	s_cselect_b32 s28, s12, s22
	s_cselect_b32 s25, s17, s51
	s_cselect_b32 s24, s16, s50
	v_lshl_add_u64 v[140:141], s[18:19], 0, v[136:137]
	s_add_i32 m0, s39, 0xc000
	ds_read_b128 v[180:183], v160
	ds_read_b128 v[184:187], v160 offset:1024
	ds_read_b128 v[188:191], v160 offset:2048
	ds_read_b128 v[194:197], v160 offset:3072
	ds_read_b128 v[198:201], v160 offset:4096
	ds_read_b128 v[202:205], v160 offset:5120
	ds_read_b128 v[206:209], v160 offset:6144
	ds_read_b128 v[210:213], v160 offset:7168
	global_load_lds_dwordx4 v[140:141], off
	v_lshl_add_u64 v[140:141], s[18:19], 0, v[138:139]
	s_add_i32 m0, s39, 0xe000
	s_nop 0
	global_load_lds_dwordx4 v[140:141], off
	s_waitcnt lgkmcnt(8)
	s_barrier
	s_waitcnt lgkmcnt(0)
	s_setprio 1
	s_waitcnt lgkmcnt(0)
	v_mfma_f32_16x16x32_bf16 v[124:127], v[162:165], v[180:183], v[124:127]
	v_mfma_f32_16x16x32_bf16 v[120:123], v[170:173], v[180:183], v[120:123]
	v_mfma_f32_16x16x32_bf16 v[108:111], v[162:165], v[188:191], v[108:111]
	v_mfma_f32_16x16x32_bf16 v[104:107], v[170:173], v[188:191], v[104:107]
	v_mfma_f32_16x16x32_bf16 v[92:95], v[162:165], v[198:201], v[92:95]
	v_mfma_f32_16x16x32_bf16 v[88:91], v[170:173], v[198:201], v[88:91]
	v_mfma_f32_16x16x32_bf16 v[76:79], v[162:165], v[206:209], v[76:79]
	v_mfma_f32_16x16x32_bf16 v[72:75], v[170:173], v[206:209], v[72:75]
	v_mfma_f32_16x16x32_bf16 v[124:127], v[166:169], v[184:187], v[124:127]
	v_mfma_f32_16x16x32_bf16 v[120:123], v[176:179], v[184:187], v[120:123]
	v_mfma_f32_16x16x32_bf16 v[108:111], v[166:169], v[194:197], v[108:111]
	v_mfma_f32_16x16x32_bf16 v[104:107], v[176:179], v[194:197], v[104:107]
	v_mfma_f32_16x16x32_bf16 v[92:95], v[166:169], v[202:205], v[92:95]
	v_mfma_f32_16x16x32_bf16 v[88:91], v[176:179], v[202:205], v[88:91]
	v_mfma_f32_16x16x32_bf16 v[76:79], v[166:169], v[210:213], v[76:79]
	v_mfma_f32_16x16x32_bf16 v[72:75], v[176:179], v[210:213], v[72:75]
	s_setprio 0
	s_barrier
	s_add_i32 s54, 0, 0x14000
	v_add_u32_e32 v140, s54, v144
	s_add_i32 s18, s53, s38
	ds_read_b128 v[214:217], v140
	ds_read_b128 v[218:221], v140 offset:1024
	ds_read_b128 v[222:225], v140 offset:2048
	ds_read_b128 v[226:229], v140 offset:3072
	v_lshl_add_u64 v[140:141], s[24:25], 0, v[128:129]
	s_mov_b32 m0, s18
	v_lshl_add_u64 v[230:231], s[24:25], 0, v[132:133]
	global_load_lds_dwordx4 v[140:141], off
	s_add_i32 m0, s18, 0x2000
	s_nop 0
	global_load_lds_dwordx4 v[230:231], off
	s_barrier
	s_waitcnt lgkmcnt(0)
	s_setprio 1
	s_waitcnt lgkmcnt(0)
	v_mfma_f32_16x16x32_bf16 v[116:119], v[214:217], v[180:183], v[116:119]
	v_mfma_f32_16x16x32_bf16 v[112:115], v[222:225], v[180:183], v[112:115]
	v_mfma_f32_16x16x32_bf16 v[100:103], v[214:217], v[188:191], v[100:103]
	v_mfma_f32_16x16x32_bf16 v[96:99], v[222:225], v[188:191], v[96:99]
	v_mfma_f32_16x16x32_bf16 v[84:87], v[214:217], v[198:201], v[84:87]
	v_mfma_f32_16x16x32_bf16 v[80:83], v[222:225], v[198:201], v[80:83]
	v_mfma_f32_16x16x32_bf16 v[68:71], v[214:217], v[206:209], v[68:71]
	v_mfma_f32_16x16x32_bf16 v[64:67], v[222:225], v[206:209], v[64:67]
	v_mfma_f32_16x16x32_bf16 v[116:119], v[218:221], v[184:187], v[116:119]
	v_mfma_f32_16x16x32_bf16 v[112:115], v[226:229], v[184:187], v[112:115]
	v_mfma_f32_16x16x32_bf16 v[100:103], v[218:221], v[194:197], v[100:103]
	v_mfma_f32_16x16x32_bf16 v[96:99], v[226:229], v[194:197], v[96:99]
	v_mfma_f32_16x16x32_bf16 v[84:87], v[218:221], v[202:205], v[84:87]
	v_mfma_f32_16x16x32_bf16 v[80:83], v[226:229], v[202:205], v[80:83]
	v_mfma_f32_16x16x32_bf16 v[68:71], v[218:221], v[210:213], v[68:71]
	v_mfma_f32_16x16x32_bf16 v[64:67], v[226:229], v[210:213], v[64:67]
	s_setprio 0
	s_mov_b32 m0, s39
	v_lshl_add_u64 v[232:233], s[28:29], 0, v[128:129]
	s_barrier
	ds_read_b128 v[180:183], v160 offset:16384
	ds_read_b128 v[184:187], v160 offset:17408
	ds_read_b128 v[188:191], v160 offset:18432
	ds_read_b128 v[194:197], v160 offset:19456
	ds_read_b128 v[198:201], v160 offset:20480
	ds_read_b128 v[202:205], v160 offset:21504
	ds_read_b128 v[206:209], v160 offset:22528
	ds_read_b128 v[210:213], v160 offset:23552
	global_load_lds_dwordx4 v[232:233], off
	v_lshl_add_u64 v[234:235], s[28:29], 0, v[132:133]
	s_mov_b32 m0, s40
	s_nop 0
	global_load_lds_dwordx4 v[234:235], off
	s_barrier
	s_waitcnt lgkmcnt(0)
	s_setprio 1
	s_waitcnt lgkmcnt(0)
	v_mfma_f32_16x16x32_bf16 v[60:63], v[162:165], v[180:183], v[60:63]
	v_mfma_f32_16x16x32_bf16 v[56:59], v[170:173], v[180:183], v[56:59]
	v_mfma_f32_16x16x32_bf16 v[44:47], v[162:165], v[188:191], v[44:47]
	v_mfma_f32_16x16x32_bf16 v[40:43], v[170:173], v[188:191], v[40:43]
	v_mfma_f32_16x16x32_bf16 v[28:31], v[162:165], v[198:201], v[28:31]
	v_mfma_f32_16x16x32_bf16 v[24:27], v[170:173], v[198:201], v[24:27]
	v_mfma_f32_16x16x32_bf16 v[12:15], v[162:165], v[206:209], v[12:15]
	v_mfma_f32_16x16x32_bf16 v[8:11], v[170:173], v[206:209], v[8:11]
	v_mfma_f32_16x16x32_bf16 v[60:63], v[166:169], v[184:187], v[60:63]
	v_mfma_f32_16x16x32_bf16 v[56:59], v[176:179], v[184:187], v[56:59]
	v_mfma_f32_16x16x32_bf16 v[44:47], v[166:169], v[194:197], v[44:47]
	v_mfma_f32_16x16x32_bf16 v[40:43], v[176:179], v[194:197], v[40:43]
	v_mfma_f32_16x16x32_bf16 v[28:31], v[166:169], v[202:205], v[28:31]
	v_mfma_f32_16x16x32_bf16 v[24:27], v[176:179], v[202:205], v[24:27]
	v_mfma_f32_16x16x32_bf16 v[12:15], v[166:169], v[210:213], v[12:15]
	v_mfma_f32_16x16x32_bf16 v[8:11], v[176:179], v[210:213], v[8:11]
	s_setprio 0
	s_barrier
; #define G_STAGE(bufoff, gbase, voff) do { _Pragma("unroll") for (int _i = 0; _i < 2; ++_i) \
;         __builtin_amdgcn_global_load_lds((const unsigned*)((const char*)(gbase) + (voff)[_i]), (LAS unsigned*)(lds + (bufoff) + ldsw + _i * 8192), 16, 0, 0); } while (0)
; #define G_LDA(dst, b, h) do { _Pragma("unroll") for (int m = 0; m < 4; ++m) _Pragma("unroll") for (int k = 0; k < 2; ++k) dst[m][k] = *(const LAS bf16x8*)(lds + G_SA(b, h) + aoff + m * 2048 + k * 1024); } while (0)
; #define G_LDB(dst, b, h) do { _Pragma("unroll") for (int n = 0; n < 2; ++n) _Pragma("unroll") for (int k = 0; k < 2; ++k) dst[n][k] = *(const LAS bf16x8*)(lds + G_SB(b, h) + boff + n * 2048 + k * 1024); } while (0)
; #define G_WAIT_V(n) asm volatile("s_waitcnt vmcnt(" #n ")" ::: "memory")
; #define G_WAIT_L(n) asm volatile("s_waitcnt lgkmcnt(" #n ")" ::: "memory")
; #define G_BAR __builtin_amdgcn_s_barrier()
; #define G_SCHED __builtin_amdgcn_sched_barrier(0)
; template <bool PERM, class Dec, class Epi>
; DI void gemm_phase(LAS unsigned char* lds, const int nM, const int nN, const int K, const int lda, const int ldb, const Dec& dec, const Epi& epi, const int vb, const int panel = -1) {
;     ...
;             G_LDB(B0, 0, 0); G_SCHED; G_LDA(At, 0, 0); G_STAGE(G_SA(1, 1), a1 + hstepA, voffA);
;             G_WAIT_L(8); G_BAR; G_WAIT_L(0); G_MMA(0, 0, At, B0); G_BAR; G_SCHED;
;             G_LDB(B1, 0, 1); G_STAGE(G_SB(0, 0), b2, voffB);
;             G_BAR; G_WAIT_L(0); G_MMA(0, 1, At, B1); G_BAR;
;             G_LDA(At, 0, 1); G_STAGE(G_SA(0, 0), a2, voffA);
;             G_BAR; G_WAIT_L(0); G_MMA(1, 0, At, B0); G_BAR; G_SCHED;
;             G_STAGE(G_SB(0, 1), b2 + hstepB, voffB);
;             G_WAIT_V(6); G_BAR; G_MMA(1, 1, At, B1); G_BAR;
;             G_LDB(B0, 1, 0); G_SCHED; G_LDA(At, 1, 0); G_STAGE(G_SA(0, 1), a2 + hstepA, voffA);
;             G_WAIT_L(8); G_BAR; G_WAIT_L(0); G_MMA(0, 0, At, B0); G_BAR; G_SCHED;
;             G_LDB(B1, 1, 1); G_STAGE(G_SB(1, 0), b3, voffB);
;             G_BAR; G_WAIT_L(0); G_MMA(0, 1, At, B1); G_BAR;
;             G_LDA(At, 1, 1); G_STAGE(G_SA(1, 0), a3, voffA);
;             G_BAR; G_WAIT_L(0); G_MMA(1, 0, At, B0); G_BAR; G_SCHED;
;             G_STAGE(G_SB(1, 1), b3 + hstepB, voffB);
;             G_WAIT_V(6); G_BAR; G_MMA(1, 1, At, B1); G_BAR;
	s_add_u32 s18, s24, 0x60000
	s_addc_u32 s19, s25, 0
	s_add_i32 s53, s54, s38
	v_lshl_add_u64 v[162:163], s[18:19], 0, v[128:129]
	s_mov_b32 m0, s53
	s_nop 0
	global_load_lds_dwordx4 v[162:163], off
	v_lshl_add_u64 v[162:163], s[18:19], 0, v[132:133]
	s_add_i32 m0, s53, 0x2000
	s_nop 0
	global_load_lds_dwordx4 v[162:163], off
	s_waitcnt vmcnt(6)
	s_barrier
	s_setprio 1
	v_mfma_f32_16x16x32_bf16 v[52:55], v[214:217], v[180:183], v[52:55]
	v_mfma_f32_16x16x32_bf16 v[48:51], v[222:225], v[180:183], v[48:51]
	v_mfma_f32_16x16x32_bf16 v[36:39], v[214:217], v[188:191], v[36:39]
	v_mfma_f32_16x16x32_bf16 v[32:35], v[222:225], v[188:191], v[32:35]
	v_mfma_f32_16x16x32_bf16 v[20:23], v[214:217], v[198:201], v[20:23]
	v_mfma_f32_16x16x32_bf16 v[16:19], v[222:225], v[198:201], v[16:19]
	v_mfma_f32_16x16x32_bf16 v[4:7], v[214:217], v[206:209], v[4:7]
	v_mfma_f32_16x16x32_bf16 v[0:3], v[222:225], v[206:209], v[0:3]
	v_mfma_f32_16x16x32_bf16 v[52:55], v[218:221], v[184:187], v[52:55]
	v_mfma_f32_16x16x32_bf16 v[48:51], v[226:229], v[184:187], v[48:51]
	v_mfma_f32_16x16x32_bf16 v[36:39], v[218:221], v[194:197], v[36:39]
	v_mfma_f32_16x16x32_bf16 v[32:35], v[226:229], v[194:197], v[32:35]
	v_mfma_f32_16x16x32_bf16 v[20:23], v[218:221], v[202:205], v[20:23]
	v_mfma_f32_16x16x32_bf16 v[16:19], v[226:229], v[202:205], v[16:19]
	v_mfma_f32_16x16x32_bf16 v[4:7], v[218:221], v[210:213], v[4:7]
	v_mfma_f32_16x16x32_bf16 v[0:3], v[226:229], v[210:213], v[0:3]
	s_setprio 0
	s_add_i32 s53, 0, 0x18000
	v_add_u32_e32 v161, s53, v144
	s_barrier
	ds_read_b128 v[162:165], v161
	ds_read_b128 v[166:169], v161 offset:1024
	ds_read_b128 v[170:173], v161 offset:2048
	ds_read_b128 v[176:179], v161 offset:3072
	s_add_u32 s18, s28, 0x60000
	s_addc_u32 s19, s29, 0
	s_mov_b32 m0, s41
	v_lshl_add_u64 v[214:215], s[18:19], 0, v[128:129]
	ds_read_b128 v[180:183], v160 offset:32768
	ds_read_b128 v[184:187], v160 offset:33792
	ds_read_b128 v[188:191], v160 offset:34816
	ds_read_b128 v[194:197], v160 offset:35840
	ds_read_b128 v[198:201], v160 offset:36864
	ds_read_b128 v[202:205], v160 offset:37888
	ds_read_b128 v[206:209], v160 offset:38912
	ds_read_b128 v[210:213], v160 offset:39936
	global_load_lds_dwordx4 v[214:215], off
	v_lshl_add_u64 v[214:215], s[18:19], 0, v[132:133]
	s_mov_b32 m0, s42
	s_nop 0
	global_load_lds_dwordx4 v[214:215], off
	s_waitcnt lgkmcnt(8)
	s_barrier
	s_waitcnt lgkmcnt(0)
	s_setprio 1
	s_waitcnt lgkmcnt(0)
	v_mfma_f32_16x16x32_bf16 v[124:127], v[162:165], v[180:183], v[124:127]
	v_mfma_f32_16x16x32_bf16 v[120:123], v[170:173], v[180:183], v[120:123]
	v_mfma_f32_16x16x32_bf16 v[108:111], v[162:165], v[188:191], v[108:111]
	v_mfma_f32_16x16x32_bf16 v[104:107], v[170:173], v[188:191], v[104:107]
	v_mfma_f32_16x16x32_bf16 v[92:95], v[162:165], v[198:201], v[92:95]
	v_mfma_f32_16x16x32_bf16 v[88:91], v[170:173], v[198:201], v[88:91]
	v_mfma_f32_16x16x32_bf16 v[76:79], v[162:165], v[206:209], v[76:79]
	v_mfma_f32_16x16x32_bf16 v[72:75], v[170:173], v[206:209], v[72:75]
	v_mfma_f32_16x16x32_bf16 v[124:127], v[166:169], v[184:187], v[124:127]
	v_mfma_f32_16x16x32_bf16 v[120:123], v[176:179], v[184:187], v[120:123]
	v_mfma_f32_16x16x32_bf16 v[108:111], v[166:169], v[194:197], v[108:111]
	v_mfma_f32_16x16x32_bf16 v[104:107], v[176:179], v[194:197], v[104:107]
	v_mfma_f32_16x16x32_bf16 v[92:95], v[166:169], v[202:205], v[92:95]
	v_mfma_f32_16x16x32_bf16 v[88:91], v[176:179], v[202:205], v[88:91]
	v_mfma_f32_16x16x32_bf16 v[76:79], v[166:169], v[210:213], v[76:79]
	v_mfma_f32_16x16x32_bf16 v[72:75], v[176:179], v[210:213], v[72:75]
	s_setprio 0
	s_barrier
	s_add_i32 s28, 0, 0x1c000
	s_add_i32 s18, s53, s38
	v_add_u32_e32 v161, s28, v144
	v_lshl_add_u64 v[140:141], v[140:141], 0, s[2:3]
	s_mov_b32 m0, s18
	ds_read_b128 v[214:217], v161
	ds_read_b128 v[218:221], v161 offset:1024
	ds_read_b128 v[222:225], v161 offset:2048
	ds_read_b128 v[226:229], v161 offset:3072
	global_load_lds_dwordx4 v[140:141], off
	v_lshl_add_u64 v[140:141], v[230:231], 0, s[2:3]
	s_add_i32 m0, s18, 0x2000
	s_nop 0
	global_load_lds_dwordx4 v[140:141], off
	s_barrier
	s_waitcnt lgkmcnt(0)
	s_setprio 1
	s_waitcnt lgkmcnt(0)
	v_mfma_f32_16x16x32_bf16 v[116:119], v[214:217], v[180:183], v[116:119]
	v_mfma_f32_16x16x32_bf16 v[112:115], v[222:225], v[180:183], v[112:115]
	v_mfma_f32_16x16x32_bf16 v[100:103], v[214:217], v[188:191], v[100:103]
	v_mfma_f32_16x16x32_bf16 v[96:99], v[222:225], v[188:191], v[96:99]
	v_mfma_f32_16x16x32_bf16 v[84:87], v[214:217], v[198:201], v[84:87]
	v_mfma_f32_16x16x32_bf16 v[80:83], v[222:225], v[198:201], v[80:83]
	v_mfma_f32_16x16x32_bf16 v[68:71], v[214:217], v[206:209], v[68:71]
	v_mfma_f32_16x16x32_bf16 v[64:67], v[222:225], v[206:209], v[64:67]
	v_mfma_f32_16x16x32_bf16 v[116:119], v[218:221], v[184:187], v[116:119]
	v_mfma_f32_16x16x32_bf16 v[112:115], v[226:229], v[184:187], v[112:115]
	v_mfma_f32_16x16x32_bf16 v[100:103], v[218:221], v[194:197], v[100:103]
	v_mfma_f32_16x16x32_bf16 v[96:99], v[226:229], v[194:197], v[96:99]
	v_mfma_f32_16x16x32_bf16 v[84:87], v[218:221], v[202:205], v[84:87]
	v_mfma_f32_16x16x32_bf16 v[80:83], v[226:229], v[202:205], v[80:83]
	v_mfma_f32_16x16x32_bf16 v[68:71], v[218:221], v[210:213], v[68:71]
	v_mfma_f32_16x16x32_bf16 v[64:67], v[226:229], v[210:213], v[64:67]
	s_setprio 0
	s_mov_b32 m0, s43
	v_lshl_add_u64 v[140:141], v[232:233], 0, s[2:3]
	s_barrier
	ds_read_b128 v[180:183], v160 offset:49152
	ds_read_b128 v[184:187], v160 offset:50176
	ds_read_b128 v[188:191], v160 offset:51200
	ds_read_b128 v[194:197], v160 offset:52224
	ds_read_b128 v[198:201], v160 offset:53248
	ds_read_b128 v[202:205], v160 offset:54272
	ds_read_b128 v[206:209], v160 offset:55296
	ds_read_b128 v[210:213], v160 offset:56320
	global_load_lds_dwordx4 v[140:141], off
	v_lshl_add_u64 v[140:141], v[234:235], 0, s[2:3]
	s_mov_b32 m0, s44
	s_nop 0
	global_load_lds_dwordx4 v[140:141], off
	s_barrier
; #define G_STAGE(bufoff, gbase, voff) do { _Pragma("unroll") for (int _i = 0; _i < 2; ++_i) \
;         __builtin_amdgcn_global_load_lds((const unsigned*)((const char*)(gbase) + (voff)[_i]), (LAS unsigned*)(lds + (bufoff) + ldsw + _i * 8192), 16, 0, 0); } while (0)
; #define G_LDA(dst, b, h) do { _Pragma("unroll") for (int m = 0; m < 4; ++m) _Pragma("unroll") for (int k = 0; k < 2; ++k) dst[m][k] = *(const LAS bf16x8*)(lds + G_SA(b, h) + aoff + m * 2048 + k * 1024); } while (0)
; #define G_MMA(ai, bj, At, Bt) do { __builtin_amdgcn_s_setprio(1); _Pragma("unroll") for (int m = 0; m < 4; ++m) _Pragma("unroll") for (int n = 0; n < 2; ++n) _Pragma("unroll") for (int k = 0; k < 2; ++k) \
;         acc[ai][bj][m][n] = __builtin_amdgcn_mfma_f32_16x16x32_bf16(Bt[n][k], At[m][k], acc[ai][bj][m][n], 0, 0, 0); __builtin_amdgcn_s_setprio(0); } while (0)
; #define G_WAIT_V(n) asm volatile("s_waitcnt vmcnt(" #n ")" ::: "memory")
; #define G_WAIT_L(n) asm volatile("s_waitcnt lgkmcnt(" #n ")" ::: "memory")
; #define G_BAR __builtin_amdgcn_s_barrier()
; #define G_SCHED __builtin_amdgcn_sched_barrier(0)
; template <bool PERM, class Dec, class Epi>
; DI void gemm_phase(LAS unsigned char* lds, const int nM, const int nN, const int K, const int lda, const int ldb, const Dec& dec, const Epi& epi, const int vb, const int panel = -1) {
;     ...
;             G_BAR; G_WAIT_L(0); G_MMA(0, 1, At, B1); G_BAR;
;             G_LDA(At, 1, 1); G_STAGE(G_SA(1, 0), a3, voffA);
;             G_BAR; G_WAIT_L(0); G_MMA(1, 0, At, B0); G_BAR; G_SCHED;
;             G_STAGE(G_SB(1, 1), b3 + hstepB, voffB);
;             G_WAIT_V(6); G_BAR; G_MMA(1, 1, At, B1); G_BAR;
;         }
; __global__ void __launch_bounds__(512) hybrid_fwd(Params p) {
;     ...
;                       for (int m = 0; m < 4; ++m) { const int rl = ai * 128 + wr * 64 + m * 16 + fr; const size_t ro = (size_t)(pm * 256 + rl) * 1024 + pn * 256 + wc * 32 + 4 * fq;
;                           float ssq = 0.f;
; #pragma unroll
;                           for (int bj = 0; bj < 2; ++bj)
; #pragma unroll
;                               for (int n = 0; n < 2; ++n) { const size_t o = ro + bj * 128 + n * 16; const u32x2 xb = *(const u32x2*)(U + o);
	s_waitcnt lgkmcnt(0)
	s_setprio 1
	s_waitcnt lgkmcnt(0)
	v_mfma_f32_16x16x32_bf16 v[60:63], v[162:165], v[180:183], v[60:63]
	v_mfma_f32_16x16x32_bf16 v[56:59], v[170:173], v[180:183], v[56:59]
	v_mfma_f32_16x16x32_bf16 v[44:47], v[162:165], v[188:191], v[44:47]
	v_mfma_f32_16x16x32_bf16 v[40:43], v[170:173], v[188:191], v[40:43]
	v_mfma_f32_16x16x32_bf16 v[28:31], v[162:165], v[198:201], v[28:31]
	v_mfma_f32_16x16x32_bf16 v[24:27], v[170:173], v[198:201], v[24:27]
	v_mfma_f32_16x16x32_bf16 v[12:15], v[162:165], v[206:209], v[12:15]
	v_mfma_f32_16x16x32_bf16 v[8:11], v[170:173], v[206:209], v[8:11]
	v_mfma_f32_16x16x32_bf16 v[60:63], v[166:169], v[184:187], v[60:63]
	v_mfma_f32_16x16x32_bf16 v[56:59], v[176:179], v[184:187], v[56:59]
	v_mfma_f32_16x16x32_bf16 v[44:47], v[166:169], v[194:197], v[44:47]
	v_mfma_f32_16x16x32_bf16 v[40:43], v[176:179], v[194:197], v[40:43]
	v_mfma_f32_16x16x32_bf16 v[28:31], v[166:169], v[202:205], v[28:31]
	v_mfma_f32_16x16x32_bf16 v[24:27], v[176:179], v[202:205], v[24:27]
	v_mfma_f32_16x16x32_bf16 v[12:15], v[166:169], v[210:213], v[12:15]
	v_mfma_f32_16x16x32_bf16 v[8:11], v[176:179], v[210:213], v[8:11]
	s_setprio 0
	s_barrier
	s_add_u32 s18, s24, 0x60080
	s_addc_u32 s19, s25, 0
	s_add_i32 s24, s28, s38
	v_lshl_add_u64 v[140:141], s[18:19], 0, v[128:129]
	s_mov_b32 m0, s24
	s_nop 0
	global_load_lds_dwordx4 v[140:141], off
	v_lshl_add_u64 v[140:141], s[18:19], 0, v[132:133]
	s_add_i32 m0, s24, 0x2000
	s_nop 0
	global_load_lds_dwordx4 v[140:141], off
	s_waitcnt vmcnt(6)
	s_barrier
	s_setprio 1
	v_mfma_f32_16x16x32_bf16 v[52:55], v[214:217], v[180:183], v[52:55]
	v_mfma_f32_16x16x32_bf16 v[48:51], v[222:225], v[180:183], v[48:51]
	v_mfma_f32_16x16x32_bf16 v[36:39], v[214:217], v[188:191], v[36:39]
	v_mfma_f32_16x16x32_bf16 v[32:35], v[222:225], v[188:191], v[32:35]
	v_mfma_f32_16x16x32_bf16 v[20:23], v[214:217], v[198:201], v[20:23]
	v_mfma_f32_16x16x32_bf16 v[16:19], v[222:225], v[198:201], v[16:19]
	v_mfma_f32_16x16x32_bf16 v[4:7], v[214:217], v[206:209], v[4:7]
	v_mfma_f32_16x16x32_bf16 v[0:3], v[222:225], v[206:209], v[0:3]
	v_mfma_f32_16x16x32_bf16 v[52:55], v[218:221], v[184:187], v[52:55]
	v_mfma_f32_16x16x32_bf16 v[48:51], v[226:229], v[184:187], v[48:51]
	v_mfma_f32_16x16x32_bf16 v[36:39], v[218:221], v[194:197], v[36:39]
	v_mfma_f32_16x16x32_bf16 v[32:35], v[226:229], v[194:197], v[32:35]
	v_mfma_f32_16x16x32_bf16 v[20:23], v[218:221], v[202:205], v[20:23]
	v_mfma_f32_16x16x32_bf16 v[16:19], v[226:229], v[202:205], v[16:19]
	v_mfma_f32_16x16x32_bf16 v[4:7], v[218:221], v[210:213], v[4:7]
	v_mfma_f32_16x16x32_bf16 v[0:3], v[226:229], v[210:213], v[0:3]
	s_setprio 0
	s_add_i32 s52, s52, 2
	s_add_u32 s50, s50, 0x100
	s_addc_u32 s51, s51, 0
	s_cmp_gt_u32 s52, 21
	s_mov_b64 s[18:19], s[22:23]
	s_barrier
	s_cbranch_scc0 .LBB0_924
	s_lshl_b32 s22, s49, 8
	s_lshl_b32 s18, s48, 8
	v_add_u32_e32 v162, s22, v143
	s_ashr_i32 s19, s18, 31
	v_ashrrev_i32_e32 v163, 31, v162
	v_mov_b32_e32 v141, s19
	v_or_b32_e32 v140, s18, v134
	v_lshlrev_b64 v[162:163], 10, v[162:163]
	v_lshl_add_u64 v[162:163], v[140:141], 0, v[162:163]
	v_lshlrev_b64 v[164:165], 1, v[162:163]
	v_lshl_add_u64 v[162:163], s[20:21], 0, v[164:165]
	v_or_b32_e32 v168, 32, v164
	v_mov_b32_e32 v169, v165
	v_add_u32_e32 v230, s22, v143
	v_ashrrev_i32_e32 v231, 31, v230
	v_lshlrev_b64 v[230:231], 10, v[230:231]
	v_lshl_add_u64 v[230:231], v[140:141], 0, v[230:231]
	v_lshlrev_b64 v[230:231], 1, v[230:231]
	v_lshl_add_u64 v[230:231], s[20:21], 0, v[230:231]
	global_load_dwordx2 v[194:195], v[230:231], off
	global_load_dwordx2 v[196:197], v[230:231], off offset:32
	global_load_dwordx2 v[198:199], v[230:231], off offset:256
	global_load_dwordx2 v[200:201], v[230:231], off offset:288
	v_add_u32_e32 v230, s22, v146
	v_ashrrev_i32_e32 v231, 31, v230
	v_lshlrev_b64 v[230:231], 10, v[230:231]
	v_lshl_add_u64 v[230:231], v[140:141], 0, v[230:231]
	v_lshlrev_b64 v[230:231], 1, v[230:231]
	v_lshl_add_u64 v[230:231], s[20:21], 0, v[230:231]
	global_load_dwordx2 v[202:203], v[230:231], off
	global_load_dwordx2 v[204:205], v[230:231], off offset:32
	global_load_dwordx2 v[206:207], v[230:231], off offset:256
	global_load_dwordx2 v[208:209], v[230:231], off offset:288
	v_add_u32_e32 v230, s22, v148
	v_ashrrev_i32_e32 v231, 31, v230
	v_lshlrev_b64 v[230:231], 10, v[230:231]
	v_lshl_add_u64 v[230:231], v[140:141], 0, v[230:231]
	v_lshlrev_b64 v[230:231], 1, v[230:231]
	v_lshl_add_u64 v[230:231], s[20:21], 0, v[230:231]
	global_load_dwordx2 v[210:211], v[230:231], off
	global_load_dwordx2 v[212:213], v[230:231], off offset:32
	global_load_dwordx2 v[214:215], v[230:231], off offset:256
	global_load_dwordx2 v[216:217], v[230:231], off offset:288
	v_add_u32_e32 v230, s22, v150
	v_ashrrev_i32_e32 v231, 31, v230
	v_lshlrev_b64 v[230:231], 10, v[230:231]
	v_lshl_add_u64 v[230:231], v[140:141], 0, v[230:231]
	v_lshlrev_b64 v[230:231], 1, v[230:231]
	v_lshl_add_u64 v[230:231], s[20:21], 0, v[230:231]
	global_load_dwordx2 v[218:219], v[230:231], off
	global_load_dwordx2 v[220:221], v[230:231], off offset:32
	global_load_dwordx2 v[222:223], v[230:231], off offset:256
	global_load_dwordx2 v[224:225], v[230:231], off offset:288
	s_waitcnt vmcnt(12)
; DI float bflo(unsigned u) { return __uint_as_float(u << 16); }
; DI float bfhi(unsigned u) { return __uint_as_float(u & 0xffff0000u); }
; __global__ void __launch_bounds__(512) hybrid_fwd(Params p) {
;     ...
;                       for (int m = 0; m < 4; ++m) { const int rl = ai * 128 + wr * 64 + m * 16 + fr; const size_t ro = (size_t)(pm * 256 + rl) * 1024 + pn * 256 + wc * 32 + 4 * fq;
;                           float ssq = 0.f;
; #pragma unroll
;                           for (int bj = 0; bj < 2; ++bj)
; #pragma unroll
;                               for (int n = 0; n < 2; ++n) { const size_t o = ro + bj * 128 + n * 16; const u32x2 xb = *(const u32x2*)(U + o);
;                                   const f32x4 v = (f32x4){bflo(xb[0]), bfhi(xb[0]), bflo(xb[1]), bfhi(xb[1])} + acc[ai][bj][m][n];
	v_lshlrev_b32_e32 v226, 16, v194
	v_and_b32_e32 v227, 0xffff0000, v194
	v_lshlrev_b32_e32 v228, 16, v195
	v_and_b32_e32 v229, 0xffff0000, v195
	v_pk_add_f32 v[124:125], v[124:125], v[226:227]
	v_pk_add_f32 v[126:127], v[126:127], v[228:229]
	v_lshlrev_b32_e32 v226, 16, v196
	v_and_b32_e32 v227, 0xffff0000, v196
	v_lshlrev_b32_e32 v228, 16, v197
	v_and_b32_e32 v229, 0xffff0000, v197
	v_pk_add_f32 v[120:121], v[120:121], v[226:227]
	v_pk_add_f32 v[122:123], v[122:123], v[228:229]
	v_lshlrev_b32_e32 v226, 16, v198
	v_and_b32_e32 v227, 0xffff0000, v198
	v_lshlrev_b32_e32 v228, 16, v199
	v_and_b32_e32 v229, 0xffff0000, v199
	v_pk_add_f32 v[116:117], v[116:117], v[226:227]
	v_pk_add_f32 v[118:119], v[118:119], v[228:229]
	v_lshlrev_b32_e32 v226, 16, v200
	v_and_b32_e32 v227, 0xffff0000, v200
	v_lshlrev_b32_e32 v228, 16, v201
	v_and_b32_e32 v229, 0xffff0000, v201
	v_pk_add_f32 v[112:113], v[112:113], v[226:227]
	v_pk_add_f32 v[114:115], v[114:115], v[228:229]
	v_add_u32_e32 v230, s22, v152
	v_ashrrev_i32_e32 v231, 31, v230
	v_lshlrev_b64 v[230:231], 10, v[230:231]
	v_lshl_add_u64 v[230:231], v[140:141], 0, v[230:231]
	v_lshlrev_b64 v[230:231], 1, v[230:231]
	v_lshl_add_u64 v[230:231], s[20:21], 0, v[230:231]
	global_load_dwordx2 v[194:195], v[230:231], off
	global_load_dwordx2 v[196:197], v[230:231], off offset:32
	global_load_dwordx2 v[198:199], v[230:231], off offset:256
	global_load_dwordx2 v[200:201], v[230:231], off offset:288
	s_waitcnt vmcnt(12)
	v_lshlrev_b32_e32 v226, 16, v202
	v_and_b32_e32 v227, 0xffff0000, v202
	v_lshlrev_b32_e32 v228, 16, v203
	v_and_b32_e32 v229, 0xffff0000, v203
	v_pk_add_f32 v[108:109], v[108:109], v[226:227]
	v_pk_add_f32 v[110:111], v[110:111], v[228:229]
	v_lshlrev_b32_e32 v226, 16, v204
	v_and_b32_e32 v227, 0xffff0000, v204
	v_lshlrev_b32_e32 v228, 16, v205
	v_and_b32_e32 v229, 0xffff0000, v205
	v_pk_add_f32 v[104:105], v[104:105], v[226:227]
	v_pk_add_f32 v[106:107], v[106:107], v[228:229]
	v_lshlrev_b32_e32 v226, 16, v206
	v_and_b32_e32 v227, 0xffff0000, v206
	v_lshlrev_b32_e32 v228, 16, v207
	v_and_b32_e32 v229, 0xffff0000, v207
	v_pk_add_f32 v[100:101], v[100:101], v[226:227]
	v_pk_add_f32 v[102:103], v[102:103], v[228:229]
	v_lshlrev_b32_e32 v226, 16, v208
	v_and_b32_e32 v227, 0xffff0000, v208
	v_lshlrev_b32_e32 v228, 16, v209
	v_and_b32_e32 v229, 0xffff0000, v209
	v_pk_add_f32 v[96:97], v[96:97], v[226:227]
	v_pk_add_f32 v[98:99], v[98:99], v[228:229]
	v_add_u32_e32 v230, s22, v154
	v_ashrrev_i32_e32 v231, 31, v230
	v_lshlrev_b64 v[230:231], 10, v[230:231]
	v_lshl_add_u64 v[230:231], v[140:141], 0, v[230:231]
	v_lshlrev_b64 v[230:231], 1, v[230:231]
	v_lshl_add_u64 v[230:231], s[20:21], 0, v[230:231]
	global_load_dwordx2 v[202:203], v[230:231], off
	global_load_dwordx2 v[204:205], v[230:231], off offset:32
	global_load_dwordx2 v[206:207], v[230:231], off offset:256
	global_load_dwordx2 v[208:209], v[230:231], off offset:288
	s_waitcnt vmcnt(12)
	v_lshlrev_b32_e32 v226, 16, v210
	v_and_b32_e32 v227, 0xffff0000, v210
	v_lshlrev_b32_e32 v228, 16, v211
	v_and_b32_e32 v229, 0xffff0000, v211
	v_pk_add_f32 v[92:93], v[92:93], v[226:227]
	v_pk_add_f32 v[94:95], v[94:95], v[228:229]
	v_lshlrev_b32_e32 v226, 16, v212
	v_and_b32_e32 v227, 0xffff0000, v212
	v_lshlrev_b32_e32 v228, 16, v213
	v_and_b32_e32 v229, 0xffff0000, v213
	v_pk_add_f32 v[88:89], v[88:89], v[226:227]
	v_pk_add_f32 v[90:91], v[90:91], v[228:229]
	v_lshlrev_b32_e32 v226, 16, v214
	v_and_b32_e32 v227, 0xffff0000, v214
	v_lshlrev_b32_e32 v228, 16, v215
	v_and_b32_e32 v229, 0xffff0000, v215
	v_pk_add_f32 v[84:85], v[84:85], v[226:227]
	v_pk_add_f32 v[86:87], v[86:87], v[228:229]
	v_lshlrev_b32_e32 v226, 16, v216
	v_and_b32_e32 v227, 0xffff0000, v216
	v_lshlrev_b32_e32 v228, 16, v217
	v_and_b32_e32 v229, 0xffff0000, v217
	v_pk_add_f32 v[80:81], v[80:81], v[226:227]
	v_pk_add_f32 v[82:83], v[82:83], v[228:229]
	v_add_u32_e32 v230, s22, v156
	v_ashrrev_i32_e32 v231, 31, v230
	v_lshlrev_b64 v[230:231], 10, v[230:231]
	v_lshl_add_u64 v[230:231], v[140:141], 0, v[230:231]
	v_lshlrev_b64 v[230:231], 1, v[230:231]
	v_lshl_add_u64 v[230:231], s[20:21], 0, v[230:231]
	global_load_dwordx2 v[210:211], v[230:231], off
	global_load_dwordx2 v[212:213], v[230:231], off offset:32
	global_load_dwordx2 v[214:215], v[230:231], off offset:256
	global_load_dwordx2 v[216:217], v[230:231], off offset:288
	s_waitcnt vmcnt(12)
	v_lshlrev_b32_e32 v226, 16, v218
	v_and_b32_e32 v227, 0xffff0000, v218
	v_lshlrev_b32_e32 v228, 16, v219
	v_and_b32_e32 v229, 0xffff0000, v219
	v_pk_add_f32 v[76:77], v[76:77], v[226:227]
	v_pk_add_f32 v[78:79], v[78:79], v[228:229]
	v_lshlrev_b32_e32 v226, 16, v220
	v_and_b32_e32 v227, 0xffff0000, v220
	v_lshlrev_b32_e32 v228, 16, v221
	v_and_b32_e32 v229, 0xffff0000, v221
	v_pk_add_f32 v[72:73], v[72:73], v[226:227]
	v_pk_add_f32 v[74:75], v[74:75], v[228:229]
	v_lshlrev_b32_e32 v226, 16, v222
	v_and_b32_e32 v227, 0xffff0000, v222
	v_lshlrev_b32_e32 v228, 16, v223
	v_and_b32_e32 v229, 0xffff0000, v223
	v_pk_add_f32 v[68:69], v[68:69], v[226:227]
	v_pk_add_f32 v[70:71], v[70:71], v[228:229]
	v_lshlrev_b32_e32 v226, 16, v224
	v_and_b32_e32 v227, 0xffff0000, v224
	v_lshlrev_b32_e32 v228, 16, v225
	v_and_b32_e32 v229, 0xffff0000, v225
	v_pk_add_f32 v[64:65], v[64:65], v[226:227]
	v_pk_add_f32 v[66:67], v[66:67], v[228:229]
	v_add_u32_e32 v230, s22, v158
	v_ashrrev_i32_e32 v231, 31, v230
	v_lshlrev_b64 v[230:231], 10, v[230:231]
	v_lshl_add_u64 v[230:231], v[140:141], 0, v[230:231]
	v_lshlrev_b64 v[230:231], 1, v[230:231]
	v_lshl_add_u64 v[230:231], s[20:21], 0, v[230:231]
	global_load_dwordx2 v[218:219], v[230:231], off
	global_load_dwordx2 v[220:221], v[230:231], off offset:32
	global_load_dwordx2 v[222:223], v[230:231], off offset:256
	global_load_dwordx2 v[224:225], v[230:231], off offset:288
	s_waitcnt vmcnt(12)
; DI unsigned pk2(float a, float b) { f32x2 v = {a, b}; bf2_t r = __builtin_convertvector(v, bf2_t); return __builtin_bit_cast(unsigned, r); }
; DI float bflo(unsigned u) { return __uint_as_float(u << 16); }
; DI float bfhi(unsigned u) { return __uint_as_float(u & 0xffff0000u); }
; __global__ void __launch_bounds__(512) hybrid_fwd(Params p) {
;     ...
;                               for (int n = 0; n < 2; ++n) { const size_t o = ro + bj * 128 + n * 16; const u32x2 xb = *(const u32x2*)(U + o);
;                                   const f32x4 v = (f32x4){bflo(xb[0]), bfhi(xb[0]), bflo(xb[1]), bfhi(xb[1])} + acc[ai][bj][m][n];
;                                   u32x2 wv; wv[0] = pk2(v[0], v[1]); wv[1] = pk2(v[2], v[3]); *(u32x2*)(X2B + o) = wv;
;                                   ssq += v[0] * v[0] + v[1] * v[1] + v[2] * v[2] + v[3] * v[3]; }
;                           ssq += __shfl_xor(ssq, 16); ssq += __shfl_xor(ssq, 32);
;                           if (fq == 0) __hip_atomic_fetch_add((float*)(shm + 131072) + rl, ssq, __ATOMIC_RELAXED, __HIP_MEMORY_SCOPE_WORKGROUP); } }, vb, panel);
	v_lshlrev_b32_e32 v226, 16, v194
	v_and_b32_e32 v227, 0xffff0000, v194
	v_lshlrev_b32_e32 v228, 16, v195
	v_and_b32_e32 v229, 0xffff0000, v195
	v_pk_add_f32 v[60:61], v[60:61], v[226:227]
	v_pk_add_f32 v[62:63], v[62:63], v[228:229]
	v_lshlrev_b32_e32 v226, 16, v196
	v_and_b32_e32 v227, 0xffff0000, v196
	v_lshlrev_b32_e32 v228, 16, v197
	v_and_b32_e32 v229, 0xffff0000, v197
	v_pk_add_f32 v[56:57], v[56:57], v[226:227]
	v_pk_add_f32 v[58:59], v[58:59], v[228:229]
	v_lshlrev_b32_e32 v226, 16, v198
	v_and_b32_e32 v227, 0xffff0000, v198
	v_lshlrev_b32_e32 v228, 16, v199
	v_and_b32_e32 v229, 0xffff0000, v199
	v_pk_add_f32 v[52:53], v[52:53], v[226:227]
	v_pk_add_f32 v[54:55], v[54:55], v[228:229]
	v_lshlrev_b32_e32 v226, 16, v200
	v_and_b32_e32 v227, 0xffff0000, v200
	v_lshlrev_b32_e32 v228, 16, v201
	v_and_b32_e32 v229, 0xffff0000, v201
	v_pk_add_f32 v[48:49], v[48:49], v[226:227]
	v_pk_add_f32 v[50:51], v[50:51], v[228:229]
	s_waitcnt vmcnt(8)
	v_lshlrev_b32_e32 v226, 16, v202
	v_and_b32_e32 v227, 0xffff0000, v202
	v_lshlrev_b32_e32 v228, 16, v203
	v_and_b32_e32 v229, 0xffff0000, v203
	v_pk_add_f32 v[44:45], v[44:45], v[226:227]
	v_pk_add_f32 v[46:47], v[46:47], v[228:229]
	v_lshlrev_b32_e32 v226, 16, v204
	v_and_b32_e32 v227, 0xffff0000, v204
	v_lshlrev_b32_e32 v228, 16, v205
	v_and_b32_e32 v229, 0xffff0000, v205
	v_pk_add_f32 v[40:41], v[40:41], v[226:227]
	v_pk_add_f32 v[42:43], v[42:43], v[228:229]
	v_lshlrev_b32_e32 v226, 16, v206
	v_and_b32_e32 v227, 0xffff0000, v206
	v_lshlrev_b32_e32 v228, 16, v207
	v_and_b32_e32 v229, 0xffff0000, v207
	v_pk_add_f32 v[36:37], v[36:37], v[226:227]
	v_pk_add_f32 v[38:39], v[38:39], v[228:229]
	v_lshlrev_b32_e32 v226, 16, v208
	v_and_b32_e32 v227, 0xffff0000, v208
	v_lshlrev_b32_e32 v228, 16, v209
	v_and_b32_e32 v229, 0xffff0000, v209
	v_pk_add_f32 v[32:33], v[32:33], v[226:227]
	v_pk_add_f32 v[34:35], v[34:35], v[228:229]
	s_waitcnt vmcnt(4)
	v_lshlrev_b32_e32 v226, 16, v210
	v_and_b32_e32 v227, 0xffff0000, v210
	v_lshlrev_b32_e32 v228, 16, v211
	v_and_b32_e32 v229, 0xffff0000, v211
	v_pk_add_f32 v[28:29], v[28:29], v[226:227]
	v_pk_add_f32 v[30:31], v[30:31], v[228:229]
	v_lshlrev_b32_e32 v226, 16, v212
	v_and_b32_e32 v227, 0xffff0000, v212
	v_lshlrev_b32_e32 v228, 16, v213
	v_and_b32_e32 v229, 0xffff0000, v213
	v_pk_add_f32 v[24:25], v[24:25], v[226:227]
	v_pk_add_f32 v[26:27], v[26:27], v[228:229]
	v_lshlrev_b32_e32 v226, 16, v214
	v_and_b32_e32 v227, 0xffff0000, v214
	v_lshlrev_b32_e32 v228, 16, v215
	v_and_b32_e32 v229, 0xffff0000, v215
	v_pk_add_f32 v[20:21], v[20:21], v[226:227]
	v_pk_add_f32 v[22:23], v[22:23], v[228:229]
	v_lshlrev_b32_e32 v226, 16, v216
	v_and_b32_e32 v227, 0xffff0000, v216
	v_lshlrev_b32_e32 v228, 16, v217
	v_and_b32_e32 v229, 0xffff0000, v217
	v_pk_add_f32 v[16:17], v[16:17], v[226:227]
	v_pk_add_f32 v[18:19], v[18:19], v[228:229]
	s_waitcnt vmcnt(0)
	v_lshlrev_b32_e32 v226, 16, v218
	v_and_b32_e32 v227, 0xffff0000, v218
	v_lshlrev_b32_e32 v228, 16, v219
	v_and_b32_e32 v229, 0xffff0000, v219
	v_pk_add_f32 v[12:13], v[12:13], v[226:227]
	v_pk_add_f32 v[14:15], v[14:15], v[228:229]
	v_lshlrev_b32_e32 v226, 16, v220
	v_and_b32_e32 v227, 0xffff0000, v220
	v_lshlrev_b32_e32 v228, 16, v221
	v_and_b32_e32 v229, 0xffff0000, v221
	v_pk_add_f32 v[8:9], v[8:9], v[226:227]
	v_pk_add_f32 v[10:11], v[10:11], v[228:229]
	v_lshlrev_b32_e32 v226, 16, v222
	v_and_b32_e32 v227, 0xffff0000, v222
	v_lshlrev_b32_e32 v228, 16, v223
	v_and_b32_e32 v229, 0xffff0000, v223
	v_pk_add_f32 v[4:5], v[4:5], v[226:227]
	v_pk_add_f32 v[6:7], v[6:7], v[228:229]
	v_lshlrev_b32_e32 v226, 16, v224
	v_and_b32_e32 v227, 0xffff0000, v224
	v_lshlrev_b32_e32 v228, 16, v225
	v_and_b32_e32 v229, 0xffff0000, v225
	v_pk_add_f32 v[0:1], v[0:1], v[226:227]
	v_pk_add_f32 v[2:3], v[2:3], v[228:229]
	v_mbcnt_lo_u32_b32 v220, -1, 0
	v_mbcnt_hi_u32_b32 v220, -1, v220
	v_and_b32_e32 v218, 1, v220
	v_lshlrev_b32_e32 v218, 5, v218
	v_bfe_u32 v219, v220, 1, 1
	v_lshl_or_b32 v218, v219, 4, v218
	v_lshrrev_b32_e32 v220, 2, v220
	v_add_lshl_u32 v220, v220, v218, 2
	v_mbcnt_lo_u32_b32 v218, -1, 0
	v_mbcnt_hi_u32_b32 v218, -1, v218
	v_bfe_u32 v218, v218, 4, 1
	v_mul_u32_u24_e32 v218, 24, v218
	v_mov_b32_e32 v219, 0
	v_lshl_add_u64 v[162:163], s[20:21], 0, v[168:169]
	v_or_b32_e32 v172, 0x100, v164
	v_mov_b32_e32 v173, v165
	v_lshl_add_u64 v[162:163], s[20:21], 0, v[172:173]
	v_lshl_add_u64 v[178:179], s[58:59], 0, v[164:165]
	v_or_b32_e32 v164, 0x120, v164
	v_lshl_add_u64 v[162:163], s[20:21], 0, v[164:165]
	v_and_b32_e32 v162, 64, v174
	v_xor_b32_e32 v161, 16, v174
	v_add_u32_e32 v162, 64, v162
	v_xor_b32_e32 v163, 32, v174
	v_cmp_lt_i32_e32 vcc, v161, v162
	v_lshl_add_u64 v[168:169], s[58:59], 0, v[168:169]
	v_lshlrev_b32_e32 v182, 16, v166
	v_and_b32_e32 v183, 0xffff0000, v166
	v_lshlrev_b32_e32 v166, 16, v167
	v_and_b32_e32 v167, 0xffff0000, v167
	v_lshlrev_b32_e32 v166, 16, v170
	v_and_b32_e32 v167, 0xffff0000, v170
	v_lshlrev_b32_e32 v182, 16, v176
	v_and_b32_e32 v183, 0xffff0000, v176
	v_lshlrev_b32_e32 v184, 16, v180
	v_and_b32_e32 v185, 0xffff0000, v180
	v_cndmask_b32_e32 v161, v174, v161, vcc
	v_cmp_lt_i32_e32 vcc, v163, v162
	v_lshlrev_b32_e32 v170, 16, v171
	v_and_b32_e32 v171, 0xffff0000, v171
	v_cvt_pk_bf16_f32 v186, v124, v125
	v_mul_f32_e32 v125, v125, v125
	v_mov_b32_e32 v166, v112
	v_mov_b32_e32 v167, v113
	v_cvt_pk_bf16_f32 v112, v120, v121
	v_mul_f32_e32 v121, v121, v121
	v_cndmask_b32_e32 v163, v174, v163, vcc
	v_lshlrev_b32_e32 v176, 16, v177
	v_and_b32_e32 v177, 0xffff0000, v177
	v_fmac_f32_e32 v125, v124, v124
	v_mul_f32_e32 v124, v117, v117
	v_fmac_f32_e32 v121, v120, v120
	v_lshlrev_b32_e32 v162, 2, v161
	v_lshlrev_b32_e32 v161, 2, v163
	v_lshlrev_b32_e32 v180, 16, v181
	v_and_b32_e32 v181, 0xffff0000, v181
	v_mul_f32_e32 v163, v167, v167
	v_fmac_f32_e32 v125, v126, v126
	v_fmac_f32_e32 v124, v116, v116
	v_fmac_f32_e32 v121, v122, v122
	v_cvt_pk_bf16_f32 v113, v122, v123
	v_fmac_f32_e32 v163, v166, v166
	v_fmac_f32_e32 v125, v127, v127
	v_fmac_f32_e32 v124, v118, v118
	v_fmac_f32_e32 v121, v123, v123
	v_mov_b32_e32 v198, v112
	v_mov_b32_e32 v199, v113
	v_fmac_f32_e32 v163, v114, v114
	v_fmac_f32_e32 v124, v119, v119
	v_add_f32_e32 v112, v125, v121
	v_add_f32_e32 v112, v112, v124
	v_fmac_f32_e32 v163, v115, v115
	v_add_f32_e32 v120, v112, v163
	ds_bpermute_b32 v121, v162, v120
	v_cvt_pk_bf16_f32 v112, v116, v117
	v_cvt_pk_bf16_f32 v113, v118, v119
	v_lshl_add_u64 v[116:117], s[58:59], 0, v[172:173]
	v_mov_b32_e32 v200, v112
	v_mov_b32_e32 v201, v113
	v_lshl_add_u64 v[204:205], v[116:117], 0, v[218:219]
	s_waitcnt lgkmcnt(0)
; DI unsigned pk2(float a, float b) { f32x2 v = {a, b}; bf2_t r = __builtin_convertvector(v, bf2_t); return __builtin_bit_cast(unsigned, r); }
; DI float bflo(unsigned u) { return __uint_as_float(u << 16); }
; DI float bfhi(unsigned u) { return __uint_as_float(u & 0xffff0000u); }
; __global__ void __launch_bounds__(512) hybrid_fwd(Params p) {
;     ...
;                               for (int n = 0; n < 2; ++n) { const size_t o = ro + bj * 128 + n * 16; const u32x2 xb = *(const u32x2*)(U + o);
;                                   const f32x4 v = (f32x4){bflo(xb[0]), bfhi(xb[0]), bflo(xb[1]), bfhi(xb[1])} + acc[ai][bj][m][n];
;                                   u32x2 wv; wv[0] = pk2(v[0], v[1]); wv[1] = pk2(v[2], v[3]); *(u32x2*)(X2B + o) = wv;
;                                   ssq += v[0] * v[0] + v[1] * v[1] + v[2] * v[2] + v[3] * v[3]; }
;                           ssq += __shfl_xor(ssq, 16); ssq += __shfl_xor(ssq, 32);
;                           if (fq == 0) __hip_atomic_fetch_add((float*)(shm + 131072) + rl, ssq, __ATOMIC_RELAXED, __HIP_MEMORY_SCOPE_WORKGROUP); } }, vb, panel);
	v_add_f32_e32 v112, v120, v121
	ds_bpermute_b32 v113, v161, v112
	v_cvt_pk_bf16_f32 v187, v126, v127
	v_cvt_pk_bf16_f32 v116, v166, v167
	v_cvt_pk_bf16_f32 v117, v114, v115
	v_lshl_add_u64 v[114:115], s[58:59], 0, v[164:165]
	v_mov_b32_e32 v196, v186
	v_mov_b32_e32 v197, v187
	v_lshl_add_u64 v[194:195], v[178:179], 0, v[218:219]
	s_nop 1
	v_permlane16_swap_b32_e32 v196, v198
	v_permlane16_swap_b32_e32 v197, v199
	ds_bpermute_b32 v196, v220, v196
	ds_bpermute_b32 v197, v220, v197
	ds_bpermute_b32 v198, v220, v198
	ds_bpermute_b32 v199, v220, v199
	ds_bpermute_b32 v194, v220, v194
	ds_bpermute_b32 v195, v220, v195
	s_waitcnt lgkmcnt(0)
	global_store_dwordx4 v[194:195], v[196:199], off
	v_mov_b32_e32 v202, v116
	v_mov_b32_e32 v203, v117
	s_nop 1
	v_permlane16_swap_b32_e32 v200, v202
	v_permlane16_swap_b32_e32 v201, v203
	ds_bpermute_b32 v200, v220, v200
	ds_bpermute_b32 v201, v220, v201
	ds_bpermute_b32 v202, v220, v202
	ds_bpermute_b32 v203, v220, v203
	ds_bpermute_b32 v204, v220, v204
	ds_bpermute_b32 v205, v220, v205
	s_waitcnt lgkmcnt(0)
	global_store_dwordx4 v[204:205], v[200:203], off
	s_and_saveexec_b64 s[18:19], s[0:1]
	s_cbranch_execz .LBB0_927
	s_waitcnt lgkmcnt(0)
	v_add_f32_e32 v112, v112, v113
	ds_add_f32 v145, v112
.LBB0_927:
	s_or_b64 exec, exec, s[18:19]
	v_add_u32_e32 v112, s22, v146
	s_waitcnt lgkmcnt(0)
	v_ashrrev_i32_e32 v113, 31, v112
	v_lshlrev_b64 v[112:113], 10, v[112:113]
	v_lshl_add_u64 v[112:113], v[140:141], 0, v[112:113]
	v_lshlrev_b64 v[112:113], 1, v[112:113]
	v_lshl_add_u64 v[114:115], s[20:21], 0, v[112:113]
	v_or_b32_e32 v116, 32, v112
	v_mov_b32_e32 v117, v113
	v_lshl_add_u64 v[118:119], s[20:21], 0, v[116:117]
	v_or_b32_e32 v120, 0x100, v112
	v_mov_b32_e32 v121, v113
	v_lshl_add_u64 v[124:125], s[58:59], 0, v[112:113]
	v_or_b32_e32 v112, 0x120, v112
	v_lshl_add_u64 v[122:123], s[20:21], 0, v[120:121]
	v_lshl_add_u64 v[126:127], s[20:21], 0, v[112:113]
	v_lshl_add_u64 v[116:117], s[58:59], 0, v[116:117]
	v_lshlrev_b32_e32 v164, 16, v114
	v_and_b32_e32 v165, 0xffff0000, v114
	v_lshlrev_b32_e32 v114, 16, v115
	v_and_b32_e32 v115, 0xffff0000, v115
	v_lshlrev_b32_e32 v114, 16, v118
	v_and_b32_e32 v115, 0xffff0000, v118
	v_lshlrev_b32_e32 v164, 16, v122
	v_and_b32_e32 v165, 0xffff0000, v122
	v_lshlrev_b32_e32 v166, 16, v126
	v_and_b32_e32 v167, 0xffff0000, v126
	v_lshlrev_b32_e32 v118, 16, v119
	v_and_b32_e32 v119, 0xffff0000, v119
	v_cvt_pk_bf16_f32 v168, v108, v109
	v_mul_f32_e32 v109, v109, v109
	v_mov_b32_e32 v114, v96
	v_mov_b32_e32 v115, v97
	v_cvt_pk_bf16_f32 v96, v104, v105
	v_mul_f32_e32 v105, v105, v105
	v_lshlrev_b32_e32 v122, 16, v123
	v_and_b32_e32 v123, 0xffff0000, v123
	v_fmac_f32_e32 v109, v108, v108
	v_mul_f32_e32 v108, v101, v101
	v_fmac_f32_e32 v105, v104, v104
	v_lshlrev_b32_e32 v126, 16, v127
	v_and_b32_e32 v127, 0xffff0000, v127
	v_mul_f32_e32 v118, v115, v115
	v_fmac_f32_e32 v109, v110, v110
	v_fmac_f32_e32 v108, v100, v100
	v_fmac_f32_e32 v105, v106, v106
	v_cvt_pk_bf16_f32 v97, v106, v107
	v_fmac_f32_e32 v118, v114, v114
	v_fmac_f32_e32 v109, v111, v111
	v_fmac_f32_e32 v108, v102, v102
	v_fmac_f32_e32 v105, v107, v107
	v_mov_b32_e32 v210, v96
	v_mov_b32_e32 v211, v97
	v_fmac_f32_e32 v118, v98, v98
	v_fmac_f32_e32 v108, v103, v103
	v_add_f32_e32 v96, v109, v105
	v_add_f32_e32 v96, v96, v108
	v_fmac_f32_e32 v118, v99, v99
	v_add_f32_e32 v104, v96, v118
	ds_bpermute_b32 v105, v162, v104
	v_cvt_pk_bf16_f32 v96, v100, v101
	v_cvt_pk_bf16_f32 v97, v102, v103
	v_lshl_add_u64 v[100:101], s[58:59], 0, v[120:121]
	v_mov_b32_e32 v212, v96
	v_mov_b32_e32 v213, v97
	v_lshl_add_u64 v[216:217], v[100:101], 0, v[218:219]
	s_waitcnt lgkmcnt(0)
	v_add_f32_e32 v96, v104, v105
	ds_bpermute_b32 v97, v161, v96
	v_cvt_pk_bf16_f32 v169, v110, v111
	v_cvt_pk_bf16_f32 v100, v114, v115
	v_cvt_pk_bf16_f32 v101, v98, v99
	v_lshl_add_u64 v[98:99], s[58:59], 0, v[112:113]
	v_mov_b32_e32 v208, v168
	v_mov_b32_e32 v209, v169
	v_lshl_add_u64 v[206:207], v[124:125], 0, v[218:219]
	s_nop 1
	v_permlane16_swap_b32_e32 v208, v210
	v_permlane16_swap_b32_e32 v209, v211
	ds_bpermute_b32 v208, v220, v208
	ds_bpermute_b32 v209, v220, v209
	ds_bpermute_b32 v210, v220, v210
	ds_bpermute_b32 v211, v220, v211
	ds_bpermute_b32 v206, v220, v206
	ds_bpermute_b32 v207, v220, v207
	s_waitcnt lgkmcnt(0)
	global_store_dwordx4 v[206:207], v[208:211], off
	v_mov_b32_e32 v214, v100
	v_mov_b32_e32 v215, v101
	s_nop 1
	v_permlane16_swap_b32_e32 v212, v214
	v_permlane16_swap_b32_e32 v213, v215
	ds_bpermute_b32 v212, v220, v212
	ds_bpermute_b32 v213, v220, v213
	ds_bpermute_b32 v214, v220, v214
	ds_bpermute_b32 v215, v220, v215
	ds_bpermute_b32 v216, v220, v216
	ds_bpermute_b32 v217, v220, v217
	s_waitcnt lgkmcnt(0)
	global_store_dwordx4 v[216:217], v[212:215], off
	s_and_saveexec_b64 s[18:19], s[0:1]
	s_cbranch_execz .LBB0_929
	s_waitcnt lgkmcnt(0)
	v_add_f32_e32 v96, v96, v97
	ds_add_f32 v147, v96
; DI unsigned pk2(float a, float b) { f32x2 v = {a, b}; bf2_t r = __builtin_convertvector(v, bf2_t); return __builtin_bit_cast(unsigned, r); }
; DI float bflo(unsigned u) { return __uint_as_float(u << 16); }
; DI float bfhi(unsigned u) { return __uint_as_float(u & 0xffff0000u); }
; __global__ void __launch_bounds__(512) hybrid_fwd(Params p) {
;     ...
;                               for (int n = 0; n < 2; ++n) { const size_t o = ro + bj * 128 + n * 16; const u32x2 xb = *(const u32x2*)(U + o);
;                                   const f32x4 v = (f32x4){bflo(xb[0]), bfhi(xb[0]), bflo(xb[1]), bfhi(xb[1])} + acc[ai][bj][m][n];
;                                   u32x2 wv; wv[0] = pk2(v[0], v[1]); wv[1] = pk2(v[2], v[3]); *(u32x2*)(X2B + o) = wv;
;                                   ssq += v[0] * v[0] + v[1] * v[1] + v[2] * v[2] + v[3] * v[3]; }
;                           ssq += __shfl_xor(ssq, 16); ssq += __shfl_xor(ssq, 32);
;                           if (fq == 0) __hip_atomic_fetch_add((float*)(shm + 131072) + rl, ssq, __ATOMIC_RELAXED, __HIP_MEMORY_SCOPE_WORKGROUP); } }, vb, panel);
.LBB0_929:
	s_or_b64 exec, exec, s[18:19]
	v_add_u32_e32 v96, s22, v148
	s_waitcnt lgkmcnt(0)
	v_ashrrev_i32_e32 v97, 31, v96
	v_lshlrev_b64 v[96:97], 10, v[96:97]
	v_lshl_add_u64 v[96:97], v[140:141], 0, v[96:97]
	v_lshlrev_b64 v[96:97], 1, v[96:97]
	v_lshl_add_u64 v[98:99], s[20:21], 0, v[96:97]
	v_or_b32_e32 v100, 32, v96
	v_mov_b32_e32 v101, v97
	v_lshl_add_u64 v[102:103], s[20:21], 0, v[100:101]
	v_or_b32_e32 v104, 0x100, v96
	v_mov_b32_e32 v105, v97
	v_lshl_add_u64 v[108:109], s[58:59], 0, v[96:97]
	v_or_b32_e32 v96, 0x120, v96
	v_lshl_add_u64 v[106:107], s[20:21], 0, v[104:105]
	v_lshl_add_u64 v[110:111], s[20:21], 0, v[96:97]
	v_lshl_add_u64 v[100:101], s[58:59], 0, v[100:101]
	v_lshlrev_b32_e32 v112, 16, v98
	v_and_b32_e32 v113, 0xffff0000, v98
	v_lshlrev_b32_e32 v98, 16, v99
	v_and_b32_e32 v99, 0xffff0000, v99
	v_lshlrev_b32_e32 v98, 16, v102
	v_and_b32_e32 v99, 0xffff0000, v102
	v_lshlrev_b32_e32 v112, 16, v106
	v_and_b32_e32 v113, 0xffff0000, v106
	v_lshlrev_b32_e32 v114, 16, v110
	v_and_b32_e32 v115, 0xffff0000, v110
	v_lshlrev_b32_e32 v102, 16, v103
	v_and_b32_e32 v103, 0xffff0000, v103
	v_cvt_pk_bf16_f32 v116, v92, v93
	v_mul_f32_e32 v93, v93, v93
	v_mov_b32_e32 v98, v80
	v_mov_b32_e32 v99, v81
	v_cvt_pk_bf16_f32 v80, v88, v89
	v_mul_f32_e32 v89, v89, v89
	v_lshlrev_b32_e32 v106, 16, v107
	v_and_b32_e32 v107, 0xffff0000, v107
	v_fmac_f32_e32 v93, v92, v92
	v_mul_f32_e32 v92, v85, v85
	v_fmac_f32_e32 v89, v88, v88
	v_lshlrev_b32_e32 v110, 16, v111
	v_and_b32_e32 v111, 0xffff0000, v111
	v_mul_f32_e32 v102, v99, v99
	v_fmac_f32_e32 v93, v94, v94
	v_fmac_f32_e32 v92, v84, v84
	v_fmac_f32_e32 v89, v90, v90
	v_cvt_pk_bf16_f32 v81, v90, v91
	v_fmac_f32_e32 v102, v98, v98
	v_fmac_f32_e32 v93, v95, v95
	v_fmac_f32_e32 v92, v86, v86
	v_fmac_f32_e32 v89, v91, v91
	v_mov_b32_e32 v198, v80
	v_mov_b32_e32 v199, v81
	v_fmac_f32_e32 v102, v82, v82
	v_fmac_f32_e32 v92, v87, v87
	v_add_f32_e32 v80, v93, v89
	v_add_f32_e32 v80, v80, v92
	v_fmac_f32_e32 v102, v83, v83
	v_add_f32_e32 v88, v80, v102
	ds_bpermute_b32 v89, v162, v88
	v_cvt_pk_bf16_f32 v80, v84, v85
	v_cvt_pk_bf16_f32 v81, v86, v87
	v_lshl_add_u64 v[84:85], s[58:59], 0, v[104:105]
	v_mov_b32_e32 v200, v80
	v_mov_b32_e32 v201, v81
	v_lshl_add_u64 v[204:205], v[84:85], 0, v[218:219]
	s_waitcnt lgkmcnt(0)
	v_add_f32_e32 v80, v88, v89
	ds_bpermute_b32 v81, v161, v80
	v_cvt_pk_bf16_f32 v117, v94, v95
	v_cvt_pk_bf16_f32 v84, v98, v99
	v_cvt_pk_bf16_f32 v85, v82, v83
	v_lshl_add_u64 v[82:83], s[58:59], 0, v[96:97]
	v_mov_b32_e32 v196, v116
	v_mov_b32_e32 v197, v117
	v_lshl_add_u64 v[194:195], v[108:109], 0, v[218:219]
	s_nop 1
	v_permlane16_swap_b32_e32 v196, v198
	v_permlane16_swap_b32_e32 v197, v199
	ds_bpermute_b32 v196, v220, v196
	ds_bpermute_b32 v197, v220, v197
	ds_bpermute_b32 v198, v220, v198
	ds_bpermute_b32 v199, v220, v199
	ds_bpermute_b32 v194, v220, v194
	ds_bpermute_b32 v195, v220, v195
	s_waitcnt lgkmcnt(0)
	global_store_dwordx4 v[194:195], v[196:199], off
	v_mov_b32_e32 v202, v84
	v_mov_b32_e32 v203, v85
	s_nop 1
	v_permlane16_swap_b32_e32 v200, v202
	v_permlane16_swap_b32_e32 v201, v203
	ds_bpermute_b32 v200, v220, v200
	ds_bpermute_b32 v201, v220, v201
	ds_bpermute_b32 v202, v220, v202
	ds_bpermute_b32 v203, v220, v203
	ds_bpermute_b32 v204, v220, v204
	ds_bpermute_b32 v205, v220, v205
	s_waitcnt lgkmcnt(0)
	global_store_dwordx4 v[204:205], v[200:203], off
	s_and_saveexec_b64 s[18:19], s[0:1]
	s_cbranch_execz .LBB0_931
	s_waitcnt lgkmcnt(0)
	v_add_f32_e32 v80, v80, v81
	ds_add_f32 v149, v80
.LBB0_931:
	s_or_b64 exec, exec, s[18:19]
	v_add_u32_e32 v80, s22, v150
	s_waitcnt lgkmcnt(0)
	v_ashrrev_i32_e32 v81, 31, v80
	v_lshlrev_b64 v[80:81], 10, v[80:81]
	v_lshl_add_u64 v[80:81], v[140:141], 0, v[80:81]
	v_lshlrev_b64 v[80:81], 1, v[80:81]
	v_lshl_add_u64 v[82:83], s[20:21], 0, v[80:81]
	v_or_b32_e32 v84, 32, v80
	v_mov_b32_e32 v85, v81
	v_lshl_add_u64 v[86:87], s[20:21], 0, v[84:85]
	v_or_b32_e32 v88, 0x100, v80
	v_mov_b32_e32 v89, v81
	v_lshl_add_u64 v[92:93], s[58:59], 0, v[80:81]
	v_or_b32_e32 v80, 0x120, v80
	v_lshl_add_u64 v[90:91], s[20:21], 0, v[88:89]
	v_lshl_add_u64 v[94:95], s[20:21], 0, v[80:81]
	v_lshl_add_u64 v[84:85], s[58:59], 0, v[84:85]
	v_lshlrev_b32_e32 v96, 16, v82
	v_and_b32_e32 v97, 0xffff0000, v82
	v_lshlrev_b32_e32 v82, 16, v83
	v_and_b32_e32 v83, 0xffff0000, v83
	v_lshlrev_b32_e32 v82, 16, v86
	v_and_b32_e32 v83, 0xffff0000, v86
	v_lshlrev_b32_e32 v96, 16, v90
	v_and_b32_e32 v97, 0xffff0000, v90
	v_lshlrev_b32_e32 v98, 16, v94
	v_and_b32_e32 v99, 0xffff0000, v94
	v_lshlrev_b32_e32 v86, 16, v87
	v_and_b32_e32 v87, 0xffff0000, v87
	v_cvt_pk_bf16_f32 v100, v76, v77
	v_mul_f32_e32 v77, v77, v77
	v_mov_b32_e32 v82, v64
	v_mov_b32_e32 v83, v65
	v_cvt_pk_bf16_f32 v64, v72, v73
	v_mul_f32_e32 v73, v73, v73
	v_lshlrev_b32_e32 v90, 16, v91
	v_and_b32_e32 v91, 0xffff0000, v91
	v_fmac_f32_e32 v77, v76, v76
	v_mul_f32_e32 v76, v69, v69
	v_fmac_f32_e32 v73, v72, v72
	v_lshlrev_b32_e32 v94, 16, v95
	v_and_b32_e32 v95, 0xffff0000, v95
	v_mul_f32_e32 v86, v83, v83
	v_fmac_f32_e32 v77, v78, v78
	v_fmac_f32_e32 v76, v68, v68
	v_fmac_f32_e32 v73, v74, v74
	v_cvt_pk_bf16_f32 v65, v74, v75
	v_fmac_f32_e32 v86, v82, v82
	v_fmac_f32_e32 v77, v79, v79
	v_fmac_f32_e32 v76, v70, v70
	v_fmac_f32_e32 v73, v75, v75
	v_mov_b32_e32 v210, v64
	v_mov_b32_e32 v211, v65
	v_fmac_f32_e32 v86, v66, v66
	v_fmac_f32_e32 v76, v71, v71
	v_add_f32_e32 v64, v77, v73
	v_add_f32_e32 v64, v64, v76
	v_fmac_f32_e32 v86, v67, v67
	v_add_f32_e32 v72, v64, v86
	ds_bpermute_b32 v73, v162, v72
	v_cvt_pk_bf16_f32 v64, v68, v69
	v_cvt_pk_bf16_f32 v65, v70, v71
	v_lshl_add_u64 v[68:69], s[58:59], 0, v[88:89]
	v_mov_b32_e32 v212, v64
	v_mov_b32_e32 v213, v65
	v_lshl_add_u64 v[216:217], v[68:69], 0, v[218:219]
	s_waitcnt lgkmcnt(0)
	v_add_f32_e32 v64, v72, v73
	ds_bpermute_b32 v65, v161, v64
	v_cvt_pk_bf16_f32 v101, v78, v79
	v_cvt_pk_bf16_f32 v68, v82, v83
	v_cvt_pk_bf16_f32 v69, v66, v67
	v_lshl_add_u64 v[66:67], s[58:59], 0, v[80:81]
	v_mov_b32_e32 v208, v100
	v_mov_b32_e32 v209, v101
	v_lshl_add_u64 v[206:207], v[92:93], 0, v[218:219]
	s_nop 1
	v_permlane16_swap_b32_e32 v208, v210
	v_permlane16_swap_b32_e32 v209, v211
	ds_bpermute_b32 v208, v220, v208
	ds_bpermute_b32 v209, v220, v209
	ds_bpermute_b32 v210, v220, v210
	ds_bpermute_b32 v211, v220, v211
	ds_bpermute_b32 v206, v220, v206
	ds_bpermute_b32 v207, v220, v207
	s_waitcnt lgkmcnt(0)
	global_store_dwordx4 v[206:207], v[208:211], off
	v_mov_b32_e32 v214, v68
	v_mov_b32_e32 v215, v69
	s_nop 1
	v_permlane16_swap_b32_e32 v212, v214
	v_permlane16_swap_b32_e32 v213, v215
	ds_bpermute_b32 v212, v220, v212
	ds_bpermute_b32 v213, v220, v213
	ds_bpermute_b32 v214, v220, v214
	ds_bpermute_b32 v215, v220, v215
	ds_bpermute_b32 v216, v220, v216
	ds_bpermute_b32 v217, v220, v217
	s_waitcnt lgkmcnt(0)
	global_store_dwordx4 v[216:217], v[212:215], off
	s_and_saveexec_b64 s[18:19], s[0:1]
	s_cbranch_execz .LBB0_933
	s_waitcnt lgkmcnt(0)
	v_add_f32_e32 v64, v64, v65
	ds_add_f32 v151, v64
; DI unsigned pk2(float a, float b) { f32x2 v = {a, b}; bf2_t r = __builtin_convertvector(v, bf2_t); return __builtin_bit_cast(unsigned, r); }
; DI float bflo(unsigned u) { return __uint_as_float(u << 16); }
; DI float bfhi(unsigned u) { return __uint_as_float(u & 0xffff0000u); }
; __global__ void __launch_bounds__(512) hybrid_fwd(Params p) {
;     ...
;                               for (int n = 0; n < 2; ++n) { const size_t o = ro + bj * 128 + n * 16; const u32x2 xb = *(const u32x2*)(U + o);
;                                   const f32x4 v = (f32x4){bflo(xb[0]), bfhi(xb[0]), bflo(xb[1]), bfhi(xb[1])} + acc[ai][bj][m][n];
;                                   u32x2 wv; wv[0] = pk2(v[0], v[1]); wv[1] = pk2(v[2], v[3]); *(u32x2*)(X2B + o) = wv;
;                                   ssq += v[0] * v[0] + v[1] * v[1] + v[2] * v[2] + v[3] * v[3]; }
;                           ssq += __shfl_xor(ssq, 16); ssq += __shfl_xor(ssq, 32);
;                           if (fq == 0) __hip_atomic_fetch_add((float*)(shm + 131072) + rl, ssq, __ATOMIC_RELAXED, __HIP_MEMORY_SCOPE_WORKGROUP); } }, vb, panel);
.LBB0_933:
	s_or_b64 exec, exec, s[18:19]
	v_add_u32_e32 v64, s22, v152
	s_waitcnt lgkmcnt(0)
	v_ashrrev_i32_e32 v65, 31, v64
	v_lshlrev_b64 v[64:65], 10, v[64:65]
	v_lshl_add_u64 v[64:65], v[140:141], 0, v[64:65]
	v_lshlrev_b64 v[64:65], 1, v[64:65]
	v_lshl_add_u64 v[66:67], s[20:21], 0, v[64:65]
	v_or_b32_e32 v68, 32, v64
	v_mov_b32_e32 v69, v65
	v_lshl_add_u64 v[70:71], s[20:21], 0, v[68:69]
	v_or_b32_e32 v72, 0x100, v64
	v_mov_b32_e32 v73, v65
	v_lshl_add_u64 v[76:77], s[58:59], 0, v[64:65]
	v_or_b32_e32 v64, 0x120, v64
	v_lshl_add_u64 v[74:75], s[20:21], 0, v[72:73]
	v_lshl_add_u64 v[78:79], s[20:21], 0, v[64:65]
	v_lshl_add_u64 v[68:69], s[58:59], 0, v[68:69]
	v_lshlrev_b32_e32 v80, 16, v66
	v_and_b32_e32 v81, 0xffff0000, v66
	v_lshlrev_b32_e32 v66, 16, v67
	v_and_b32_e32 v67, 0xffff0000, v67
	v_lshlrev_b32_e32 v66, 16, v70
	v_and_b32_e32 v67, 0xffff0000, v70
	v_lshlrev_b32_e32 v80, 16, v74
	v_and_b32_e32 v81, 0xffff0000, v74
	v_lshlrev_b32_e32 v82, 16, v78
	v_and_b32_e32 v83, 0xffff0000, v78
	v_lshlrev_b32_e32 v70, 16, v71
	v_and_b32_e32 v71, 0xffff0000, v71
	v_cvt_pk_bf16_f32 v84, v60, v61
	v_mul_f32_e32 v61, v61, v61
	v_mov_b32_e32 v66, v48
	v_mov_b32_e32 v67, v49
	v_cvt_pk_bf16_f32 v48, v56, v57
	v_mul_f32_e32 v57, v57, v57
	v_lshlrev_b32_e32 v74, 16, v75
	v_and_b32_e32 v75, 0xffff0000, v75
	v_fmac_f32_e32 v61, v60, v60
	v_mul_f32_e32 v60, v53, v53
	v_fmac_f32_e32 v57, v56, v56
	v_lshlrev_b32_e32 v78, 16, v79
	v_and_b32_e32 v79, 0xffff0000, v79
	v_mul_f32_e32 v70, v67, v67
	v_fmac_f32_e32 v61, v62, v62
	v_fmac_f32_e32 v60, v52, v52
	v_fmac_f32_e32 v57, v58, v58
	v_cvt_pk_bf16_f32 v49, v58, v59
	v_fmac_f32_e32 v70, v66, v66
	v_fmac_f32_e32 v61, v63, v63
	v_fmac_f32_e32 v60, v54, v54
	v_fmac_f32_e32 v57, v59, v59
	v_mov_b32_e32 v198, v48
	v_mov_b32_e32 v199, v49
	v_fmac_f32_e32 v70, v50, v50
	v_fmac_f32_e32 v60, v55, v55
	v_add_f32_e32 v48, v61, v57
	v_add_f32_e32 v48, v48, v60
	v_fmac_f32_e32 v70, v51, v51
	v_add_f32_e32 v56, v48, v70
	ds_bpermute_b32 v57, v162, v56
	v_cvt_pk_bf16_f32 v48, v52, v53
	v_cvt_pk_bf16_f32 v49, v54, v55
	v_lshl_add_u64 v[52:53], s[58:59], 0, v[72:73]
	v_mov_b32_e32 v200, v48
	v_mov_b32_e32 v201, v49
	v_lshl_add_u64 v[204:205], v[52:53], 0, v[218:219]
	s_waitcnt lgkmcnt(0)
	v_add_f32_e32 v48, v56, v57
	ds_bpermute_b32 v49, v161, v48
	v_cvt_pk_bf16_f32 v85, v62, v63
	v_cvt_pk_bf16_f32 v52, v66, v67
	v_cvt_pk_bf16_f32 v53, v50, v51
	v_lshl_add_u64 v[50:51], s[58:59], 0, v[64:65]
	v_mov_b32_e32 v196, v84
	v_mov_b32_e32 v197, v85
	v_lshl_add_u64 v[194:195], v[76:77], 0, v[218:219]
	s_nop 1
	v_permlane16_swap_b32_e32 v196, v198
	v_permlane16_swap_b32_e32 v197, v199
	ds_bpermute_b32 v196, v220, v196
	ds_bpermute_b32 v197, v220, v197
	ds_bpermute_b32 v198, v220, v198
	ds_bpermute_b32 v199, v220, v199
	ds_bpermute_b32 v194, v220, v194
	ds_bpermute_b32 v195, v220, v195
	s_waitcnt lgkmcnt(0)
	global_store_dwordx4 v[194:195], v[196:199], off
	v_mov_b32_e32 v202, v52
	v_mov_b32_e32 v203, v53
	s_nop 1
	v_permlane16_swap_b32_e32 v200, v202
	v_permlane16_swap_b32_e32 v201, v203
	ds_bpermute_b32 v200, v220, v200
	ds_bpermute_b32 v201, v220, v201
	ds_bpermute_b32 v202, v220, v202
	ds_bpermute_b32 v203, v220, v203
	ds_bpermute_b32 v204, v220, v204
	ds_bpermute_b32 v205, v220, v205
	s_waitcnt lgkmcnt(0)
	global_store_dwordx4 v[204:205], v[200:203], off
	s_and_saveexec_b64 s[18:19], s[0:1]
	s_cbranch_execz .LBB0_935
	s_waitcnt lgkmcnt(0)
	v_add_f32_e32 v48, v48, v49
	ds_add_f32 v153, v48
.LBB0_935:
	s_or_b64 exec, exec, s[18:19]
	v_add_u32_e32 v48, s22, v154
	s_waitcnt lgkmcnt(0)
	v_ashrrev_i32_e32 v49, 31, v48
	v_lshlrev_b64 v[48:49], 10, v[48:49]
	v_lshl_add_u64 v[48:49], v[140:141], 0, v[48:49]
	v_lshlrev_b64 v[48:49], 1, v[48:49]
	v_lshl_add_u64 v[50:51], s[20:21], 0, v[48:49]
	v_or_b32_e32 v52, 32, v48
	v_mov_b32_e32 v53, v49
	v_lshl_add_u64 v[54:55], s[20:21], 0, v[52:53]
	v_or_b32_e32 v56, 0x100, v48
	v_mov_b32_e32 v57, v49
	v_lshl_add_u64 v[60:61], s[58:59], 0, v[48:49]
	v_or_b32_e32 v48, 0x120, v48
	v_lshl_add_u64 v[58:59], s[20:21], 0, v[56:57]
	v_lshl_add_u64 v[62:63], s[20:21], 0, v[48:49]
	v_lshl_add_u64 v[52:53], s[58:59], 0, v[52:53]
	v_lshlrev_b32_e32 v64, 16, v50
	v_and_b32_e32 v65, 0xffff0000, v50
	v_lshlrev_b32_e32 v50, 16, v51
	v_and_b32_e32 v51, 0xffff0000, v51
	v_lshlrev_b32_e32 v50, 16, v54
	v_and_b32_e32 v51, 0xffff0000, v54
	v_lshlrev_b32_e32 v64, 16, v58
	v_and_b32_e32 v65, 0xffff0000, v58
	v_lshlrev_b32_e32 v66, 16, v62
	v_and_b32_e32 v67, 0xffff0000, v62
	v_lshlrev_b32_e32 v54, 16, v55
	v_and_b32_e32 v55, 0xffff0000, v55
	v_cvt_pk_bf16_f32 v68, v44, v45
	v_mul_f32_e32 v45, v45, v45
	v_mov_b32_e32 v50, v32
	v_mov_b32_e32 v51, v33
	v_cvt_pk_bf16_f32 v32, v40, v41
	v_mul_f32_e32 v41, v41, v41
	v_lshlrev_b32_e32 v58, 16, v59
	v_and_b32_e32 v59, 0xffff0000, v59
	v_fmac_f32_e32 v45, v44, v44
	v_mul_f32_e32 v44, v37, v37
	v_fmac_f32_e32 v41, v40, v40
	v_lshlrev_b32_e32 v62, 16, v63
	v_and_b32_e32 v63, 0xffff0000, v63
	v_mul_f32_e32 v54, v51, v51
	v_fmac_f32_e32 v45, v46, v46
	v_fmac_f32_e32 v44, v36, v36
	v_fmac_f32_e32 v41, v42, v42
	v_cvt_pk_bf16_f32 v33, v42, v43
	v_fmac_f32_e32 v54, v50, v50
	v_fmac_f32_e32 v45, v47, v47
	v_fmac_f32_e32 v44, v38, v38
	v_fmac_f32_e32 v41, v43, v43
	v_mov_b32_e32 v210, v32
	v_mov_b32_e32 v211, v33
	v_fmac_f32_e32 v54, v34, v34
	v_fmac_f32_e32 v44, v39, v39
	v_add_f32_e32 v32, v45, v41
	v_add_f32_e32 v32, v32, v44
	v_fmac_f32_e32 v54, v35, v35
	v_add_f32_e32 v40, v32, v54
	ds_bpermute_b32 v41, v162, v40
	v_cvt_pk_bf16_f32 v32, v36, v37
	v_cvt_pk_bf16_f32 v33, v38, v39
	v_lshl_add_u64 v[36:37], s[58:59], 0, v[56:57]
	v_mov_b32_e32 v212, v32
	v_mov_b32_e32 v213, v33
	v_lshl_add_u64 v[216:217], v[36:37], 0, v[218:219]
	s_waitcnt lgkmcnt(0)
	v_add_f32_e32 v32, v40, v41
	ds_bpermute_b32 v33, v161, v32
	v_cvt_pk_bf16_f32 v69, v46, v47
	v_cvt_pk_bf16_f32 v36, v50, v51
	v_cvt_pk_bf16_f32 v37, v34, v35
	v_lshl_add_u64 v[34:35], s[58:59], 0, v[48:49]
	v_mov_b32_e32 v208, v68
	v_mov_b32_e32 v209, v69
	v_lshl_add_u64 v[206:207], v[60:61], 0, v[218:219]
	s_nop 1
	v_permlane16_swap_b32_e32 v208, v210
	v_permlane16_swap_b32_e32 v209, v211
	ds_bpermute_b32 v208, v220, v208
	ds_bpermute_b32 v209, v220, v209
	ds_bpermute_b32 v210, v220, v210
	ds_bpermute_b32 v211, v220, v211
	ds_bpermute_b32 v206, v220, v206
	ds_bpermute_b32 v207, v220, v207
	s_waitcnt lgkmcnt(0)
	global_store_dwordx4 v[206:207], v[208:211], off
	v_mov_b32_e32 v214, v36
	v_mov_b32_e32 v215, v37
	s_nop 1
	v_permlane16_swap_b32_e32 v212, v214
	v_permlane16_swap_b32_e32 v213, v215
	ds_bpermute_b32 v212, v220, v212
	ds_bpermute_b32 v213, v220, v213
	ds_bpermute_b32 v214, v220, v214
	ds_bpermute_b32 v215, v220, v215
	ds_bpermute_b32 v216, v220, v216
	ds_bpermute_b32 v217, v220, v217
	s_waitcnt lgkmcnt(0)
	global_store_dwordx4 v[216:217], v[212:215], off
	s_and_saveexec_b64 s[18:19], s[0:1]
	s_cbranch_execz .LBB0_937
	s_waitcnt lgkmcnt(0)
	v_add_f32_e32 v32, v32, v33
	ds_add_f32 v155, v32
; DI unsigned pk2(float a, float b) { f32x2 v = {a, b}; bf2_t r = __builtin_convertvector(v, bf2_t); return __builtin_bit_cast(unsigned, r); }
; DI float bflo(unsigned u) { return __uint_as_float(u << 16); }
; DI float bfhi(unsigned u) { return __uint_as_float(u & 0xffff0000u); }
; __global__ void __launch_bounds__(512) hybrid_fwd(Params p) {
;     ...
;                               for (int n = 0; n < 2; ++n) { const size_t o = ro + bj * 128 + n * 16; const u32x2 xb = *(const u32x2*)(U + o);
;                                   const f32x4 v = (f32x4){bflo(xb[0]), bfhi(xb[0]), bflo(xb[1]), bfhi(xb[1])} + acc[ai][bj][m][n];
;                                   u32x2 wv; wv[0] = pk2(v[0], v[1]); wv[1] = pk2(v[2], v[3]); *(u32x2*)(X2B + o) = wv;
;                                   ssq += v[0] * v[0] + v[1] * v[1] + v[2] * v[2] + v[3] * v[3]; }
;                           ssq += __shfl_xor(ssq, 16); ssq += __shfl_xor(ssq, 32);
;                           if (fq == 0) __hip_atomic_fetch_add((float*)(shm + 131072) + rl, ssq, __ATOMIC_RELAXED, __HIP_MEMORY_SCOPE_WORKGROUP); } }, vb, panel);
.LBB0_937:
	s_or_b64 exec, exec, s[18:19]
	v_add_u32_e32 v32, s22, v156
	s_waitcnt lgkmcnt(0)
	v_ashrrev_i32_e32 v33, 31, v32
	v_lshlrev_b64 v[32:33], 10, v[32:33]
	v_lshl_add_u64 v[32:33], v[140:141], 0, v[32:33]
	v_lshlrev_b64 v[32:33], 1, v[32:33]
	v_lshl_add_u64 v[34:35], s[20:21], 0, v[32:33]
	v_or_b32_e32 v36, 32, v32
	v_mov_b32_e32 v37, v33
	v_lshl_add_u64 v[38:39], s[20:21], 0, v[36:37]
	v_or_b32_e32 v40, 0x100, v32
	v_mov_b32_e32 v41, v33
	v_lshl_add_u64 v[44:45], s[58:59], 0, v[32:33]
	v_or_b32_e32 v32, 0x120, v32
	v_lshl_add_u64 v[42:43], s[20:21], 0, v[40:41]
	v_lshl_add_u64 v[46:47], s[20:21], 0, v[32:33]
	v_lshl_add_u64 v[36:37], s[58:59], 0, v[36:37]
	v_lshlrev_b32_e32 v48, 16, v34
	v_and_b32_e32 v49, 0xffff0000, v34
	v_lshlrev_b32_e32 v34, 16, v35
	v_and_b32_e32 v35, 0xffff0000, v35
	v_lshlrev_b32_e32 v34, 16, v38
	v_and_b32_e32 v35, 0xffff0000, v38
	v_lshlrev_b32_e32 v48, 16, v42
	v_and_b32_e32 v49, 0xffff0000, v42
	v_lshlrev_b32_e32 v50, 16, v46
	v_and_b32_e32 v51, 0xffff0000, v46
	v_lshlrev_b32_e32 v38, 16, v39
	v_and_b32_e32 v39, 0xffff0000, v39
	v_cvt_pk_bf16_f32 v52, v28, v29
	v_mul_f32_e32 v29, v29, v29
	v_mov_b32_e32 v34, v16
	v_mov_b32_e32 v35, v17
	v_cvt_pk_bf16_f32 v16, v24, v25
	v_mul_f32_e32 v25, v25, v25
	v_lshlrev_b32_e32 v42, 16, v43
	v_and_b32_e32 v43, 0xffff0000, v43
	v_fmac_f32_e32 v29, v28, v28
	v_mul_f32_e32 v28, v21, v21
	v_fmac_f32_e32 v25, v24, v24
	v_lshlrev_b32_e32 v46, 16, v47
	v_and_b32_e32 v47, 0xffff0000, v47
	v_mul_f32_e32 v38, v35, v35
	v_fmac_f32_e32 v29, v30, v30
	v_fmac_f32_e32 v28, v20, v20
	v_fmac_f32_e32 v25, v26, v26
	v_cvt_pk_bf16_f32 v17, v26, v27
	v_fmac_f32_e32 v38, v34, v34
	v_fmac_f32_e32 v29, v31, v31
	v_fmac_f32_e32 v28, v22, v22
	v_fmac_f32_e32 v25, v27, v27
	v_mov_b32_e32 v198, v16
	v_mov_b32_e32 v199, v17
	v_fmac_f32_e32 v38, v18, v18
	v_fmac_f32_e32 v28, v23, v23
	v_add_f32_e32 v16, v29, v25
	v_add_f32_e32 v16, v16, v28
	v_fmac_f32_e32 v38, v19, v19
	v_add_f32_e32 v24, v16, v38
	ds_bpermute_b32 v25, v162, v24
	v_cvt_pk_bf16_f32 v16, v20, v21
	v_cvt_pk_bf16_f32 v17, v22, v23
	v_lshl_add_u64 v[20:21], s[58:59], 0, v[40:41]
	v_mov_b32_e32 v200, v16
	v_mov_b32_e32 v201, v17
	v_lshl_add_u64 v[204:205], v[20:21], 0, v[218:219]
	s_waitcnt lgkmcnt(0)
	v_add_f32_e32 v16, v24, v25
	ds_bpermute_b32 v17, v161, v16
	v_cvt_pk_bf16_f32 v53, v30, v31
	v_cvt_pk_bf16_f32 v20, v34, v35
	v_cvt_pk_bf16_f32 v21, v18, v19
	v_lshl_add_u64 v[18:19], s[58:59], 0, v[32:33]
	v_mov_b32_e32 v196, v52
	v_mov_b32_e32 v197, v53
	v_lshl_add_u64 v[194:195], v[44:45], 0, v[218:219]
	s_nop 1
	v_permlane16_swap_b32_e32 v196, v198
	v_permlane16_swap_b32_e32 v197, v199
	ds_bpermute_b32 v196, v220, v196
	ds_bpermute_b32 v197, v220, v197
	ds_bpermute_b32 v198, v220, v198
	ds_bpermute_b32 v199, v220, v199
	ds_bpermute_b32 v194, v220, v194
	ds_bpermute_b32 v195, v220, v195
	s_waitcnt lgkmcnt(0)
	global_store_dwordx4 v[194:195], v[196:199], off
	v_mov_b32_e32 v202, v20
	v_mov_b32_e32 v203, v21
	s_nop 1
	v_permlane16_swap_b32_e32 v200, v202
	v_permlane16_swap_b32_e32 v201, v203
	ds_bpermute_b32 v200, v220, v200
	ds_bpermute_b32 v201, v220, v201
	ds_bpermute_b32 v202, v220, v202
	ds_bpermute_b32 v203, v220, v203
	ds_bpermute_b32 v204, v220, v204
	ds_bpermute_b32 v205, v220, v205
	s_waitcnt lgkmcnt(0)
	global_store_dwordx4 v[204:205], v[200:203], off
	s_and_saveexec_b64 s[18:19], s[0:1]
	s_cbranch_execz .LBB0_939
	s_waitcnt lgkmcnt(0)
	v_add_f32_e32 v16, v16, v17
	ds_add_f32 v157, v16
.LBB0_939:
	s_or_b64 exec, exec, s[18:19]
	v_add_u32_e32 v16, s22, v158
	s_waitcnt lgkmcnt(0)
	v_ashrrev_i32_e32 v17, 31, v16
	v_lshlrev_b64 v[16:17], 10, v[16:17]
	v_lshl_add_u64 v[16:17], v[140:141], 0, v[16:17]
	v_lshlrev_b64 v[16:17], 1, v[16:17]
	v_lshl_add_u64 v[18:19], s[20:21], 0, v[16:17]
	v_or_b32_e32 v20, 32, v16
	v_mov_b32_e32 v21, v17
	v_lshl_add_u64 v[22:23], s[20:21], 0, v[20:21]
	v_or_b32_e32 v24, 0x100, v16
	v_mov_b32_e32 v25, v17
	v_lshl_add_u64 v[28:29], s[58:59], 0, v[16:17]
	v_or_b32_e32 v16, 0x120, v16
	v_lshl_add_u64 v[26:27], s[20:21], 0, v[24:25]
	v_lshl_add_u64 v[30:31], s[20:21], 0, v[16:17]
	v_lshl_add_u64 v[20:21], s[58:59], 0, v[20:21]
	v_lshlrev_b32_e32 v32, 16, v18
	v_and_b32_e32 v33, 0xffff0000, v18
	v_lshlrev_b32_e32 v18, 16, v19
	v_and_b32_e32 v19, 0xffff0000, v19
	v_lshlrev_b32_e32 v18, 16, v22
	v_and_b32_e32 v19, 0xffff0000, v22
	v_lshlrev_b32_e32 v32, 16, v26
	v_and_b32_e32 v33, 0xffff0000, v26
	v_lshlrev_b32_e32 v34, 16, v30
	v_and_b32_e32 v35, 0xffff0000, v30
	v_lshlrev_b32_e32 v22, 16, v23
	v_and_b32_e32 v23, 0xffff0000, v23
	v_cvt_pk_bf16_f32 v36, v12, v13
	v_mul_f32_e32 v13, v13, v13
	v_mov_b32_e32 v18, v0
	v_mov_b32_e32 v19, v1
	v_cvt_pk_bf16_f32 v0, v8, v9
	v_mul_f32_e32 v9, v9, v9
	v_lshlrev_b32_e32 v26, 16, v27
	v_and_b32_e32 v27, 0xffff0000, v27
	v_fmac_f32_e32 v13, v12, v12
	v_mul_f32_e32 v12, v5, v5
	v_fmac_f32_e32 v9, v8, v8
	v_lshlrev_b32_e32 v30, 16, v31
	v_and_b32_e32 v31, 0xffff0000, v31
	v_mul_f32_e32 v22, v19, v19
	v_fmac_f32_e32 v13, v14, v14
	v_fmac_f32_e32 v12, v4, v4
	v_fmac_f32_e32 v9, v10, v10
	v_cvt_pk_bf16_f32 v1, v10, v11
	v_fmac_f32_e32 v22, v18, v18
	v_fmac_f32_e32 v13, v15, v15
	v_fmac_f32_e32 v12, v6, v6
	v_fmac_f32_e32 v9, v11, v11
	v_mov_b32_e32 v210, v0
	v_mov_b32_e32 v211, v1
	v_fmac_f32_e32 v22, v2, v2
	v_fmac_f32_e32 v12, v7, v7
	v_add_f32_e32 v0, v13, v9
	v_add_f32_e32 v0, v0, v12
	v_fmac_f32_e32 v22, v3, v3
	v_add_f32_e32 v8, v0, v22
	ds_bpermute_b32 v9, v162, v8
	v_cvt_pk_bf16_f32 v0, v4, v5
	v_cvt_pk_bf16_f32 v1, v6, v7
	v_lshl_add_u64 v[4:5], s[58:59], 0, v[24:25]
	v_mov_b32_e32 v212, v0
	v_mov_b32_e32 v213, v1
	v_lshl_add_u64 v[216:217], v[4:5], 0, v[218:219]
	s_waitcnt lgkmcnt(0)
	v_add_f32_e32 v0, v8, v9
	ds_bpermute_b32 v1, v161, v0
	v_cvt_pk_bf16_f32 v37, v14, v15
	v_cvt_pk_bf16_f32 v4, v18, v19
	v_cvt_pk_bf16_f32 v5, v2, v3
	v_lshl_add_u64 v[2:3], s[58:59], 0, v[16:17]
	v_mov_b32_e32 v208, v36
	v_mov_b32_e32 v209, v37
	v_lshl_add_u64 v[206:207], v[28:29], 0, v[218:219]
	s_nop 1
	v_permlane16_swap_b32_e32 v208, v210
	v_permlane16_swap_b32_e32 v209, v211
	ds_bpermute_b32 v208, v220, v208
	ds_bpermute_b32 v209, v220, v209
	ds_bpermute_b32 v210, v220, v210
	ds_bpermute_b32 v211, v220, v211
	ds_bpermute_b32 v206, v220, v206
	ds_bpermute_b32 v207, v220, v207
	s_waitcnt lgkmcnt(0)
	global_store_dwordx4 v[206:207], v[208:211], off
	v_mov_b32_e32 v214, v4
	v_mov_b32_e32 v215, v5
	s_nop 1
	v_permlane16_swap_b32_e32 v212, v214
	v_permlane16_swap_b32_e32 v213, v215
	ds_bpermute_b32 v212, v220, v212
	ds_bpermute_b32 v213, v220, v213
	ds_bpermute_b32 v214, v220, v214
	ds_bpermute_b32 v215, v220, v215
	ds_bpermute_b32 v216, v220, v216
	ds_bpermute_b32 v217, v220, v217
	s_waitcnt lgkmcnt(0)
	global_store_dwordx4 v[216:217], v[212:215], off
	s_and_saveexec_b64 s[18:19], s[0:1]
	s_cbranch_execz .LBB0_915
	s_waitcnt lgkmcnt(0)
	v_add_f32_e32 v0, v0, v1
	ds_add_f32 v159, v0
	s_branch .LBB0_915
